# tail-round backfill: workgroups idle in P1's last half round transpose w_down/w_ple/w_ple_gate there instead of in P0
# speedup vs baseline: 1.0161x; 1.0053x over previous
; #define LAS __attribute__((address_space(3)))
; #define INP(i) ((const float*)(const GAS float*)KARG(8 * (i)))
; template <int KIND> __device__ __forceinline__ void tr_item(const float* __restrict__ W, int K, int Nsrc, const float* __restrict__ gk, bf16_t* WT, LAS float* scr, int item, int nblk, int lane) {
;     const int kb = item / nblk, nb = item - kb * nblk, k0 = 64 * kb, n0 = 32 * nb;
;     const int src = srcmap<KIND>(n0 + (lane & 31));
; __global__ void __launch_bounds__(512, 2) fwd(Params P) {
;     ...
;         LAS float* scr = (LAS float*)(lds + wave * 16384);
;         constexpr int I0 = (2048 / 64) * (NIN / 32), I1 = (512 / 64) * (1536 / 32), I2 = (512 / 64) * (2048 / 32), I3 = (1024 / 64) * (2048 / 32), I4 = I3,
;                       I5 = (2048 / 64) * (2048 / 32), I6 = (2048 / 64) * (8192 / 32), I7 = (8192 / 64) * (2048 / 32), I8 = (256 / 64) * (2048 / 32), I9 = I5;
;         constexpr int NITEMS = I0 + I1 + I2 + I3 + I4 + I5 + I6 + I7 + I8 + I9;
;         for (int it = gw; it < NITEMS; it += NGW) {
;             int r = it;
;             if (r < I0) { tr_item<1>(INP(4), 2048, 8256, nullptr, wb + OFF_WIN, scr, r, NIN / 32, lane); continue; } r -= I0;
.LBB0_20:
	s_or_b64 exec, exec, s[4:5]
	s_lshr_b32 s4, s12, 6
	s_lshl_b32 s5, s2, 3
	s_add_i32 s80, s5, s4
	s_lshl_b32 s82, s3, 3
	s_cmpk_gt_i32 s80, 0x547f
	v_and_b32_e32 v179, 63, v178
	s_cbranch_scc1 .LBB0_151
	v_lshlrev_b32_e32 v1, 3, v178
	s_lshl_b32 s4, s4, 14
	v_lshrrev_b32_e32 v25, 3, v179
	v_and_b32_e32 v2, 56, v1
	s_add_i32 s5, s4, 0
	v_mul_u32_u24_e32 v1, 0x84, v2
	v_lshlrev_b32_e32 v4, 2, v25
	v_lshrrev_b32_e32 v0, 5, v179
	v_add3_u32 v26, s5, v1, v4
	v_lshlrev_b32_e32 v1, 5, v178
	v_mov_b32_e32 v4, 0x1000
	v_and_b32_e32 v24, 31, v178
	v_and_or_b32 v30, v1, 32, v4
	v_mul_u32_u24_e32 v4, 0x84, v0
	v_mov_b32_e32 v3, 0
	v_or_b32_e32 v4, s4, v4
	v_lshlrev_b32_e32 v5, 2, v24
	s_add_i32 s42, s80, 0xffffcb80
	s_mov_b32 s9, 0
	v_or_b32_e32 v27, 8, v25
	v_or_b32_e32 v28, 16, v25
	v_or_b32_e32 v29, 24, v25
	v_mov_b32_e32 v1, v3
	v_add3_u32 v31, v4, v5, 0
	v_or_b32_e32 v32, 14, v0
	s_lshl_b32 s43, s42, 5
	s_lshl_b32 s44, s3, 8
	v_or_b32_e32 v33, 12, v0
	v_or_b32_e32 v34, 10, v0
	v_or_b32_e32 v35, 8, v0
	v_or_b32_e32 v36, 6, v0
	v_or_b32_e32 v37, 4, v0
	v_or_b32_e32 v38, 2, v0
	v_mul_u32_u24_e32 v39, 0x600, v0
	s_add_i32 s45, s80, 0xdf00
	v_lshlrev_b32_e32 v4, 2, v0
	v_mov_b32_e32 v5, v3
	s_mov_b64 s[10:11], 0x7680000
	s_mov_b64 s[12:13], 0x7580000
	s_mov_b64 s[14:15], 0x5580000
	s_mov_b64 s[16:17], 0x3580000
	s_mov_b64 s[18:19], 0x2d80000
	s_mov_b64 s[20:21], 0x2980000
	s_mov_b64 s[22:23], 0x2580000
	s_mov_b64 s[24:25], 0x2380000
	s_movk_i32 s46, 0x7f
	s_movk_i32 s47, 0x80
	s_mov_b64 s[26:27], 0x2200000
	s_movk_i32 s48, 0xfff
	s_mov_b32 s49, 0x8100
	s_mov_b64 s[28:29], 0x100000
	v_lshlrev_b32_e32 v6, 1, v2
	s_mov_b32 s50, s80
	s_branch .LBB0_24

; __global__ void __launch_bounds__(512, 2) fwd(Params P) {
;     ...
;         for (int it = gw; it < NITEMS; it += NGW) {
.LBB0_23:
	s_add_i32 s50, s50, s82
	s_add_i32 s42, s42, s82
	s_add_i32 s43, s43, s44
	s_add_i32 s45, s45, s82
	s_cmpk_gt_i32 s50, 0x547f
	s_cbranch_scc1 .LBB0_151

; #define LAS __attribute__((address_space(3)))
; #define INP(i) ((const float*)(const GAS float*)KARG(8 * (i)))
; template <int KIND> __device__ __forceinline__ void tr_item(const float* __restrict__ W, int K, int Nsrc, const float* __restrict__ gk, bf16_t* WT, LAS float* scr, int item, int nblk, int lane) {
;     const int kb = item / nblk, nb = item - kb * nblk, k0 = 64 * kb, n0 = 32 * nb;
;     const int src = srcmap<KIND>(n0 + (lane & 31));
; #pragma unroll 8
;     for (int i = 0; i < 32; ++i) { const int kk = 2 * i + (lane >> 5); float v = 0.f; if (src >= 0) v = __builtin_nontemporal_load(&W[(size_t)(k0 + kk) * Nsrc + src]); if (gk) v *= gk[k0 + kk]; scr[kk * 33 + (lane & 31)] = v; }
; __global__ void __launch_bounds__(512, 2) fwd(Params P) {
;     ...
;             if (r < I3) { tr_item<0>(INP(9), 1024, 2048, nullptr, wb + OFF_WSBO, scr, r, 2048 / 32, lane); continue; } r -= I3;
;             if (r < I4) { tr_item<0>(INP(10), 1024, 2048, nullptr, wb + OFF_WMLAO, scr, r, 2048 / 32, lane); continue; } r -= I4;
;             if (r < I5) { tr_item<0>(INP(11), 2048, 2048, nullptr, wb + OFF_WOUT, scr, r, 2048 / 32, lane); continue; } r -= I5;
;             if (r < I6) { tr_item<0>(INP(14), 2048, 8192, nullptr, wb + OFF_WUP, scr, r, 8192 / 32, lane); continue; } r -= I6;
;             if (r < I7) { tr_item<0>(INP(15), 8192, 2048, nullptr, wb + OFF_WDOWN, scr, r, 2048 / 32, lane); continue; } r -= I7;
;             if (r < I8) { tr_item<0>(INP(17), 256, 2048, nullptr, wb + OFF_WPLE, scr, r, 2048 / 32, lane); continue; } r -= I8;
;             tr_item<0>(INP(19), 2048, 2048, nullptr, wb + OFF_WPG, scr, r, 2048 / 32, lane);
.Lp0g_entry:
	v_readfirstlane_b32 s32, v178
	s_load_dwordx2 s[20:21], s[0:1], 0xa8
	v_lshrrev_b32_e32 v0, 5, v179
	v_and_b32_e32 v1, 31, v179
	v_lshrrev_b32_e32 v2, 3, v179
	v_and_b32_e32 v3, 7, v179
	s_lshr_b32 s32, s32, 6
	s_lshl_b32 s32, s32, 14
	v_lshlrev_b32_e32 v1, 2, v1
	v_mul_u32_u24_e32 v4, 0x84, v0
	v_mul_u32_u24_e32 v5, 0x420, v3
	v_add3_u32 v4, v4, v1, s32
	v_lshl_add_u32 v5, v2, 2, v5
	v_add_u32_e32 v5, s32, v5
	v_lshlrev_b32_e32 v3, 4, v3
	s_mov_b32 s4, s50
	s_waitcnt lgkmcnt(0)
	s_add_u32 s20, s20, 0x100000
	s_addc_u32 s21, s21, 0
	s_mov_b32 s16, 0x7580
	s_movk_i32 s15, 0x98
	s_mov_b32 s11, 13
	s_mov_b32 s12, 6
	s_mov_b32 s13, 11
	s_mov_b32 s14, 61603840
	s_cmpk_lt_u32 s4, 0x7580
	s_cselect_b32 s16, 0x7480, s16
	s_cselect_b32 s15, 0x88, s15
	s_cselect_b32 s11, 13, s11
	s_cselect_b32 s12, 6, s12
	s_cselect_b32 s13, 8, s13
	s_cselect_b32 s14, 61079552, s14
	s_cmpk_lt_u32 s4, 0x7480
	s_cselect_b32 s16, 0x5480, s16
	s_cselect_b32 s15, 0x78, s15
	s_cselect_b32 s11, 13, s11
	s_cselect_b32 s12, 6, s12
	s_cselect_b32 s13, 13, s13
	s_cselect_b32 s14, 44302336, s14
	s_cmpk_lt_u32 s4, 0x5480
	s_cselect_b32 s16, 0x3480, s16
	s_cselect_b32 s15, 0x70, s15
	s_cselect_b32 s11, 15, s11
	s_cselect_b32 s12, 8, s12
	s_cselect_b32 s13, 11, s13
	s_cselect_b32 s14, 27525120, s14
	s_cmpk_lt_u32 s4, 0x3480
	s_cselect_b32 s16, 0x2c80, s16
	s_cselect_b32 s15, 0x58, s15
	s_cselect_b32 s11, 13, s11
	s_cselect_b32 s12, 6, s12
	s_cselect_b32 s13, 11, s13
	s_cselect_b32 s14, 23330816, s14
	s_cmpk_lt_u32 s4, 0x2c80
	s_cselect_b32 s16, 0x2880, s16
	s_cselect_b32 s15, 0x50, s15
	s_cselect_b32 s11, 13, s11
	s_cselect_b32 s12, 6, s12
	s_cselect_b32 s13, 10, s13
	s_cselect_b32 s14, 21233664, s14
	s_cmpk_lt_u32 s4, 0x2880
	s_cselect_b32 s16, 0x2480, s16
	s_cselect_b32 s15, 0x48, s15
	s_cselect_b32 s11, 13, s11
	s_cselect_b32 s12, 6, s12
	s_cselect_b32 s13, 10, s13
	s_cselect_b32 s14, 19136512, s14
	s_load_dwordx2 s[6:7], s[0:1], s15
	s_sub_i32 s16, s4, s16
	s_lshl_b32 s19, 1, s12
	s_sub_i32 s19, s19, 1
	s_and_b32 s18, s16, s19
	s_lshr_b32 s17, s16, s12
	s_lshl_b32 s17, s17, 6
	s_lshl_b32 s19, s17, s11
	s_lshl_b32 s29, s18, 7
	s_add_u32 s19, s19, s29
	s_lshl_b32 s10, 2, s11
	v_lshlrev_b32_e32 v6, s11, v0
	v_add_u32_e32 v6, v6, v1
	s_lshl_b32 s29, s18, 5
	s_lshl_b32 s29, s29, s13
	s_add_u32 s29, s29, s17
	s_add_u32 s29, s29, s14
	s_lshl_b32 s29, s29, 1
	s_add_u32 s22, s20, s29
	s_addc_u32 s23, s21, 0
	s_lshl_b32 s24, 16, s13
	s_add_i32 s29, s13, 1
	v_lshlrev_b32_e32 v8, s29, v2
	v_add_u32_e32 v8, v8, v3
	s_waitcnt lgkmcnt(0)
	s_add_u32 s8, s6, s19
	s_addc_u32 s9, s7, 0
	global_load_dword v32, v6, s[8:9] nt
	s_add_u32 s8, s8, s10
	s_addc_u32 s9, s9, 0
	global_load_dword v33, v6, s[8:9] nt
	s_add_u32 s8, s8, s10
	s_addc_u32 s9, s9, 0
	global_load_dword v34, v6, s[8:9] nt
	s_add_u32 s8, s8, s10
	s_addc_u32 s9, s9, 0
	global_load_dword v35, v6, s[8:9] nt
	s_add_u32 s8, s8, s10
	s_addc_u32 s9, s9, 0
	global_load_dword v36, v6, s[8:9] nt
	s_add_u32 s8, s8, s10
	s_addc_u32 s9, s9, 0
	global_load_dword v37, v6, s[8:9] nt
	s_add_u32 s8, s8, s10
	s_addc_u32 s9, s9, 0
	global_load_dword v38, v6, s[8:9] nt
	s_add_u32 s8, s8, s10
	s_addc_u32 s9, s9, 0
	global_load_dword v39, v6, s[8:9] nt
	s_add_u32 s8, s8, s10
	s_addc_u32 s9, s9, 0
	global_load_dword v40, v6, s[8:9] nt
	s_add_u32 s8, s8, s10
	s_addc_u32 s9, s9, 0
	global_load_dword v41, v6, s[8:9] nt
	s_add_u32 s8, s8, s10
	s_addc_u32 s9, s9, 0
	global_load_dword v42, v6, s[8:9] nt
	s_add_u32 s8, s8, s10
	s_addc_u32 s9, s9, 0
	global_load_dword v43, v6, s[8:9] nt
	s_add_u32 s8, s8, s10
	s_addc_u32 s9, s9, 0
	global_load_dword v44, v6, s[8:9] nt
	s_add_u32 s8, s8, s10
	s_addc_u32 s9, s9, 0
	global_load_dword v45, v6, s[8:9] nt
	s_add_u32 s8, s8, s10
	s_addc_u32 s9, s9, 0
	global_load_dword v46, v6, s[8:9] nt
	s_add_u32 s8, s8, s10
	s_addc_u32 s9, s9, 0
	global_load_dword v47, v6, s[8:9] nt
	s_add_u32 s8, s8, s10
	s_addc_u32 s9, s9, 0
	global_load_dword v48, v6, s[8:9] nt
	s_add_u32 s8, s8, s10
	s_addc_u32 s9, s9, 0
	global_load_dword v49, v6, s[8:9] nt
	s_add_u32 s8, s8, s10
	s_addc_u32 s9, s9, 0
	global_load_dword v50, v6, s[8:9] nt
	s_add_u32 s8, s8, s10
	s_addc_u32 s9, s9, 0
	global_load_dword v51, v6, s[8:9] nt
	s_add_u32 s8, s8, s10
	s_addc_u32 s9, s9, 0
	global_load_dword v52, v6, s[8:9] nt
	s_add_u32 s8, s8, s10
	s_addc_u32 s9, s9, 0
	global_load_dword v53, v6, s[8:9] nt
	s_add_u32 s8, s8, s10
	s_addc_u32 s9, s9, 0
	global_load_dword v54, v6, s[8:9] nt
	s_add_u32 s8, s8, s10
	s_addc_u32 s9, s9, 0
	global_load_dword v55, v6, s[8:9] nt
	s_add_u32 s8, s8, s10
	s_addc_u32 s9, s9, 0
	global_load_dword v56, v6, s[8:9] nt
	s_add_u32 s8, s8, s10
	s_addc_u32 s9, s9, 0
	global_load_dword v57, v6, s[8:9] nt
	s_add_u32 s8, s8, s10
	s_addc_u32 s9, s9, 0
	global_load_dword v58, v6, s[8:9] nt
	s_add_u32 s8, s8, s10
	s_addc_u32 s9, s9, 0
	global_load_dword v59, v6, s[8:9] nt
	s_add_u32 s8, s8, s10
	s_addc_u32 s9, s9, 0
	global_load_dword v60, v6, s[8:9] nt
	s_add_u32 s8, s8, s10
	s_addc_u32 s9, s9, 0
	global_load_dword v61, v6, s[8:9] nt
	s_add_u32 s8, s8, s10
	s_addc_u32 s9, s9, 0
	global_load_dword v62, v6, s[8:9] nt
	s_add_u32 s8, s8, s10
	s_addc_u32 s9, s9, 0
	global_load_dword v63, v6, s[8:9] nt
	s_add_i32 s5, s4, s82
	s_cmpk_gt_i32 s5, 0x547f
	s_cbranch_scc1 .Lp0g_tail_a
; #define LAS __attribute__((address_space(3)))
; template <int KIND> __device__ __forceinline__ void tr_item(const float* __restrict__ W, int K, int Nsrc, const float* __restrict__ gk, bf16_t* WT, LAS float* scr, int item, int nblk, int lane) {
;     const int kb = item / nblk, nb = item - kb * nblk, k0 = 64 * kb, n0 = 32 * nb;
;     const int src = srcmap<KIND>(n0 + (lane & 31));
; #pragma unroll 8
;     for (int i = 0; i < 32; ++i) { const int kk = 2 * i + (lane >> 5); float v = 0.f; if (src >= 0) v = __builtin_nontemporal_load(&W[(size_t)(k0 + kk) * Nsrc + src]); if (gk) v *= gk[k0 + kk]; scr[kk * 33 + (lane & 31)] = v; }
;     asm volatile("s_waitcnt lgkmcnt(0)" ::: "memory");
;     const int c = lane & 7;
; #pragma unroll
;     for (int j = 0; j < 4; ++j) { const int n = (lane >> 3) + 8 * j; const LAS float* s = scr + (8 * c) * 33 + n;
	s_mov_b32 s16, 0x7580
	s_movk_i32 s15, 0x98
	s_mov_b32 s11, 13
	s_mov_b32 s12, 6
	s_mov_b32 s13, 11
	s_mov_b32 s14, 61603840
	s_cmpk_lt_u32 s5, 0x7580
	s_cselect_b32 s16, 0x7480, s16
	s_cselect_b32 s15, 0x88, s15
	s_cselect_b32 s11, 13, s11
	s_cselect_b32 s12, 6, s12
	s_cselect_b32 s13, 8, s13
	s_cselect_b32 s14, 61079552, s14
	s_cmpk_lt_u32 s5, 0x7480
	s_cselect_b32 s16, 0x5480, s16
	s_cselect_b32 s15, 0x78, s15
	s_cselect_b32 s11, 13, s11
	s_cselect_b32 s12, 6, s12
	s_cselect_b32 s13, 13, s13
	s_cselect_b32 s14, 44302336, s14
	s_cmpk_lt_u32 s5, 0x5480
	s_cselect_b32 s16, 0x3480, s16
	s_cselect_b32 s15, 0x70, s15
	s_cselect_b32 s11, 15, s11
	s_cselect_b32 s12, 8, s12
	s_cselect_b32 s13, 11, s13
	s_cselect_b32 s14, 27525120, s14
	s_cmpk_lt_u32 s5, 0x3480
	s_cselect_b32 s16, 0x2c80, s16
	s_cselect_b32 s15, 0x58, s15
	s_cselect_b32 s11, 13, s11
	s_cselect_b32 s12, 6, s12
	s_cselect_b32 s13, 11, s13
	s_cselect_b32 s14, 23330816, s14
	s_cmpk_lt_u32 s5, 0x2c80
	s_cselect_b32 s16, 0x2880, s16
	s_cselect_b32 s15, 0x50, s15
	s_cselect_b32 s11, 13, s11
	s_cselect_b32 s12, 6, s12
	s_cselect_b32 s13, 10, s13
	s_cselect_b32 s14, 21233664, s14
	s_cmpk_lt_u32 s5, 0x2880
	s_cselect_b32 s16, 0x2480, s16
	s_cselect_b32 s15, 0x48, s15
	s_cselect_b32 s11, 13, s11
	s_cselect_b32 s12, 6, s12
	s_cselect_b32 s13, 10, s13
	s_cselect_b32 s14, 19136512, s14
	s_load_dwordx2 s[6:7], s[0:1], s15
	s_sub_i32 s16, s5, s16
	s_lshl_b32 s19, 1, s12
	s_sub_i32 s19, s19, 1
	s_and_b32 s18, s16, s19
	s_lshr_b32 s17, s16, s12
	s_lshl_b32 s17, s17, 6
	s_lshl_b32 s19, s17, s11
	s_lshl_b32 s29, s18, 7
	s_add_u32 s19, s19, s29
	s_lshl_b32 s10, 2, s11
	v_lshlrev_b32_e32 v6, s11, v0
	v_add_u32_e32 v6, v6, v1
	s_lshl_b32 s29, s18, 5
	s_lshl_b32 s29, s29, s13
	s_add_u32 s29, s29, s17
	s_add_u32 s29, s29, s14
	s_lshl_b32 s29, s29, 1
	s_add_u32 s26, s20, s29
	s_addc_u32 s27, s21, 0
	s_lshl_b32 s28, 16, s13
	s_add_i32 s29, s13, 1
	v_lshlrev_b32_e32 v9, s29, v2
	v_add_u32_e32 v9, v9, v3
	s_waitcnt lgkmcnt(0)
	s_add_u32 s8, s6, s19
	s_addc_u32 s9, s7, 0
	global_load_dword v64, v6, s[8:9] nt
	s_add_u32 s8, s8, s10
	s_addc_u32 s9, s9, 0
	global_load_dword v65, v6, s[8:9] nt
	s_add_u32 s8, s8, s10
	s_addc_u32 s9, s9, 0
	global_load_dword v66, v6, s[8:9] nt
	s_add_u32 s8, s8, s10
	s_addc_u32 s9, s9, 0
	global_load_dword v67, v6, s[8:9] nt
	s_add_u32 s8, s8, s10
	s_addc_u32 s9, s9, 0
	global_load_dword v68, v6, s[8:9] nt
	s_add_u32 s8, s8, s10
	s_addc_u32 s9, s9, 0
	global_load_dword v69, v6, s[8:9] nt
	s_add_u32 s8, s8, s10
	s_addc_u32 s9, s9, 0
	global_load_dword v70, v6, s[8:9] nt
	s_add_u32 s8, s8, s10
	s_addc_u32 s9, s9, 0
	global_load_dword v71, v6, s[8:9] nt
	s_add_u32 s8, s8, s10
	s_addc_u32 s9, s9, 0
	global_load_dword v72, v6, s[8:9] nt
	s_add_u32 s8, s8, s10
	s_addc_u32 s9, s9, 0
	global_load_dword v73, v6, s[8:9] nt
	s_add_u32 s8, s8, s10
	s_addc_u32 s9, s9, 0
	global_load_dword v74, v6, s[8:9] nt
	s_add_u32 s8, s8, s10
	s_addc_u32 s9, s9, 0
	global_load_dword v75, v6, s[8:9] nt
	s_add_u32 s8, s8, s10
	s_addc_u32 s9, s9, 0
	global_load_dword v76, v6, s[8:9] nt
	s_add_u32 s8, s8, s10
	s_addc_u32 s9, s9, 0
	global_load_dword v77, v6, s[8:9] nt
	s_add_u32 s8, s8, s10
	s_addc_u32 s9, s9, 0
	global_load_dword v78, v6, s[8:9] nt
	s_add_u32 s8, s8, s10
	s_addc_u32 s9, s9, 0
	global_load_dword v79, v6, s[8:9] nt
	s_add_u32 s8, s8, s10
	s_addc_u32 s9, s9, 0
	global_load_dword v80, v6, s[8:9] nt
	s_add_u32 s8, s8, s10
	s_addc_u32 s9, s9, 0
	global_load_dword v81, v6, s[8:9] nt
	s_add_u32 s8, s8, s10
	s_addc_u32 s9, s9, 0
	global_load_dword v82, v6, s[8:9] nt
	s_add_u32 s8, s8, s10
	s_addc_u32 s9, s9, 0
	global_load_dword v83, v6, s[8:9] nt
	s_add_u32 s8, s8, s10
	s_addc_u32 s9, s9, 0
	global_load_dword v84, v6, s[8:9] nt
	s_add_u32 s8, s8, s10
	s_addc_u32 s9, s9, 0
	global_load_dword v85, v6, s[8:9] nt
	s_add_u32 s8, s8, s10
	s_addc_u32 s9, s9, 0
	global_load_dword v86, v6, s[8:9] nt
	s_add_u32 s8, s8, s10
	s_addc_u32 s9, s9, 0
	global_load_dword v87, v6, s[8:9] nt
	s_add_u32 s8, s8, s10
	s_addc_u32 s9, s9, 0
	global_load_dword v88, v6, s[8:9] nt
	s_add_u32 s8, s8, s10
	s_addc_u32 s9, s9, 0
	global_load_dword v89, v6, s[8:9] nt
	s_add_u32 s8, s8, s10
	s_addc_u32 s9, s9, 0
	global_load_dword v90, v6, s[8:9] nt
	s_add_u32 s8, s8, s10
	s_addc_u32 s9, s9, 0
	global_load_dword v91, v6, s[8:9] nt
	s_add_u32 s8, s8, s10
	s_addc_u32 s9, s9, 0
	global_load_dword v92, v6, s[8:9] nt
	s_add_u32 s8, s8, s10
	s_addc_u32 s9, s9, 0
	global_load_dword v93, v6, s[8:9] nt
	s_add_u32 s8, s8, s10
	s_addc_u32 s9, s9, 0
	global_load_dword v94, v6, s[8:9] nt
	s_add_u32 s8, s8, s10
	s_addc_u32 s9, s9, 0
	global_load_dword v95, v6, s[8:9] nt
	s_mov_b64 s[30:31], s[22:23]
	s_waitcnt vmcnt(63)
	ds_write_b32 v4, v32
	s_waitcnt vmcnt(62)
	ds_write_b32 v4, v33 offset:264
	s_waitcnt vmcnt(61)
	ds_write_b32 v4, v34 offset:528
	s_waitcnt vmcnt(60)
	ds_write_b32 v4, v35 offset:792
	s_waitcnt vmcnt(59)
	ds_write_b32 v4, v36 offset:1056
	s_waitcnt vmcnt(58)
	ds_write_b32 v4, v37 offset:1320
	s_waitcnt vmcnt(57)
	ds_write_b32 v4, v38 offset:1584
	s_waitcnt vmcnt(56)
	ds_write_b32 v4, v39 offset:1848
	s_waitcnt vmcnt(55)
	ds_write_b32 v4, v40 offset:2112
	s_waitcnt vmcnt(54)
	ds_write_b32 v4, v41 offset:2376
	s_waitcnt vmcnt(53)
	ds_write_b32 v4, v42 offset:2640
	s_waitcnt vmcnt(52)
	ds_write_b32 v4, v43 offset:2904
	s_waitcnt vmcnt(51)
	ds_write_b32 v4, v44 offset:3168
	s_waitcnt vmcnt(50)
	ds_write_b32 v4, v45 offset:3432
	s_waitcnt vmcnt(49)
	ds_write_b32 v4, v46 offset:3696
	s_waitcnt vmcnt(48)
	ds_write_b32 v4, v47 offset:3960
	s_waitcnt vmcnt(47)
	ds_write_b32 v4, v48 offset:4224
	s_waitcnt vmcnt(46)
; #define LAS __attribute__((address_space(3)))
; __device__ __forceinline__ unsigned pk2(float lo, float hi) { return pg8::cvt_pk_bf16(lo, hi); }
; template <int KIND> __device__ __forceinline__ void tr_item(const float* __restrict__ W, int K, int Nsrc, const float* __restrict__ gk, bf16_t* WT, LAS float* scr, int item, int nblk, int lane) {
;     ...
;     for (int i = 0; i < 32; ++i) { const int kk = 2 * i + (lane >> 5); float v = 0.f; if (src >= 0) v = __builtin_nontemporal_load(&W[(size_t)(k0 + kk) * Nsrc + src]); if (gk) v *= gk[k0 + kk]; scr[kk * 33 + (lane & 31)] = v; }
;     asm volatile("s_waitcnt lgkmcnt(0)" ::: "memory");
;     const int c = lane & 7;
; #pragma unroll
;     for (int j = 0; j < 4; ++j) { const int n = (lane >> 3) + 8 * j; const LAS float* s = scr + (8 * c) * 33 + n;
;         u32x4 o; o.x = pk2(s[0 * 33], s[1 * 33]); o.y = pk2(s[2 * 33], s[3 * 33]); o.z = pk2(s[4 * 33], s[5 * 33]); o.w = pk2(s[6 * 33], s[7 * 33]);
;         *(u32x4*)(WT + (size_t)(n0 + n) * K + k0 + 8 * c) = o; }
	ds_write_b32 v4, v49 offset:4488
	s_waitcnt vmcnt(45)
	ds_write_b32 v4, v50 offset:4752
	s_waitcnt vmcnt(44)
	ds_write_b32 v4, v51 offset:5016
	s_waitcnt vmcnt(43)
	ds_write_b32 v4, v52 offset:5280
	s_waitcnt vmcnt(42)
	ds_write_b32 v4, v53 offset:5544
	s_waitcnt vmcnt(41)
	ds_write_b32 v4, v54 offset:5808
	s_waitcnt vmcnt(40)
	ds_write_b32 v4, v55 offset:6072
	s_waitcnt vmcnt(39)
	ds_write_b32 v4, v56 offset:6336
	s_waitcnt vmcnt(38)
	ds_write_b32 v4, v57 offset:6600
	s_waitcnt vmcnt(37)
	ds_write_b32 v4, v58 offset:6864
	s_waitcnt vmcnt(36)
	ds_write_b32 v4, v59 offset:7128
	s_waitcnt vmcnt(35)
	ds_write_b32 v4, v60 offset:7392
	s_waitcnt vmcnt(34)
	ds_write_b32 v4, v61 offset:7656
	s_waitcnt vmcnt(33)
	ds_write_b32 v4, v62 offset:7920
	s_waitcnt vmcnt(32)
	ds_write_b32 v4, v63 offset:8184
	s_waitcnt lgkmcnt(0)
	ds_read2_b32 v[96:97], v5 offset0:0 offset1:8
	ds_read2_b32 v[98:99], v5 offset0:16 offset1:24
	ds_read2_b32 v[100:101], v5 offset0:33 offset1:41
	ds_read2_b32 v[102:103], v5 offset0:49 offset1:57
	ds_read2_b32 v[104:105], v5 offset0:66 offset1:74
	ds_read2_b32 v[106:107], v5 offset0:82 offset1:90
	ds_read2_b32 v[108:109], v5 offset0:99 offset1:107
	ds_read2_b32 v[110:111], v5 offset0:115 offset1:123
	ds_read2_b32 v[112:113], v5 offset0:132 offset1:140
	ds_read2_b32 v[114:115], v5 offset0:148 offset1:156
	ds_read2_b32 v[116:117], v5 offset0:165 offset1:173
	ds_read2_b32 v[118:119], v5 offset0:181 offset1:189
	ds_read2_b32 v[120:121], v5 offset0:198 offset1:206
	ds_read2_b32 v[122:123], v5 offset0:214 offset1:222
	ds_read2_b32 v[124:125], v5 offset0:231 offset1:239
	ds_read2_b32 v[126:127], v5 offset0:247 offset1:255
	s_waitcnt lgkmcnt(0)
	v_cvt_pk_bf16_f32 v12, v96, v100
	v_cvt_pk_bf16_f32 v13, v104, v108
	v_cvt_pk_bf16_f32 v14, v112, v116
	v_cvt_pk_bf16_f32 v15, v120, v124
	global_store_dwordx4 v8, v[12:15], s[30:31]
	s_add_u32 s30, s30, s24
	s_addc_u32 s31, s31, 0
	v_cvt_pk_bf16_f32 v16, v97, v101
	v_cvt_pk_bf16_f32 v17, v105, v109
	v_cvt_pk_bf16_f32 v18, v113, v117
	v_cvt_pk_bf16_f32 v19, v121, v125
	global_store_dwordx4 v8, v[16:19], s[30:31]
	s_add_u32 s30, s30, s24
	s_addc_u32 s31, s31, 0
	v_cvt_pk_bf16_f32 v12, v98, v102
	v_cvt_pk_bf16_f32 v13, v106, v110
	v_cvt_pk_bf16_f32 v14, v114, v118
	v_cvt_pk_bf16_f32 v15, v122, v126
	global_store_dwordx4 v8, v[12:15], s[30:31]
	s_add_u32 s30, s30, s24
	s_addc_u32 s31, s31, 0
	v_cvt_pk_bf16_f32 v16, v99, v103
	v_cvt_pk_bf16_f32 v17, v107, v111
	v_cvt_pk_bf16_f32 v18, v115, v119
	v_cvt_pk_bf16_f32 v19, v123, v127
	global_store_dwordx4 v8, v[16:19], s[30:31]
	s_mov_b32 s4, s5
.Lp0g_loop:
	s_add_i32 s5, s4, s82
	s_cmpk_gt_i32 s5, 0x547f
	s_cbranch_scc1 .Lp0g_tail_b
	s_mov_b32 s16, 0x7580
	s_movk_i32 s15, 0x98
	s_mov_b32 s11, 13
	s_mov_b32 s12, 6
	s_mov_b32 s13, 11
	s_mov_b32 s14, 61603840
	s_cmpk_lt_u32 s5, 0x7580
	s_cselect_b32 s16, 0x7480, s16
	s_cselect_b32 s15, 0x88, s15
	s_cselect_b32 s11, 13, s11
	s_cselect_b32 s12, 6, s12
	s_cselect_b32 s13, 8, s13
	s_cselect_b32 s14, 61079552, s14
	s_cmpk_lt_u32 s5, 0x7480
	s_cselect_b32 s16, 0x5480, s16
	s_cselect_b32 s15, 0x78, s15
	s_cselect_b32 s11, 13, s11
	s_cselect_b32 s12, 6, s12
	s_cselect_b32 s13, 13, s13
	s_cselect_b32 s14, 44302336, s14
	s_cmpk_lt_u32 s5, 0x5480
	s_cselect_b32 s16, 0x3480, s16
	s_cselect_b32 s15, 0x70, s15
	s_cselect_b32 s11, 15, s11
	s_cselect_b32 s12, 8, s12
	s_cselect_b32 s13, 11, s13
	s_cselect_b32 s14, 27525120, s14
	s_cmpk_lt_u32 s5, 0x3480
	s_cselect_b32 s16, 0x2c80, s16
	s_cselect_b32 s15, 0x58, s15
	s_cselect_b32 s11, 13, s11
	s_cselect_b32 s12, 6, s12
	s_cselect_b32 s13, 11, s13
	s_cselect_b32 s14, 23330816, s14
	s_cmpk_lt_u32 s5, 0x2c80
	s_cselect_b32 s16, 0x2880, s16
	s_cselect_b32 s15, 0x50, s15
	s_cselect_b32 s11, 13, s11
	s_cselect_b32 s12, 6, s12
	s_cselect_b32 s13, 10, s13
	s_cselect_b32 s14, 21233664, s14
	s_cmpk_lt_u32 s5, 0x2880
	s_cselect_b32 s16, 0x2480, s16
	s_cselect_b32 s15, 0x48, s15
	s_cselect_b32 s11, 13, s11
	s_cselect_b32 s12, 6, s12
	s_cselect_b32 s13, 10, s13
	s_cselect_b32 s14, 19136512, s14
	s_load_dwordx2 s[6:7], s[0:1], s15
	s_sub_i32 s16, s5, s16
	s_lshl_b32 s19, 1, s12
	s_sub_i32 s19, s19, 1
	s_and_b32 s18, s16, s19
	s_lshr_b32 s17, s16, s12
	s_lshl_b32 s17, s17, 6
	s_lshl_b32 s19, s17, s11
	s_lshl_b32 s29, s18, 7
	s_add_u32 s19, s19, s29
	s_lshl_b32 s10, 2, s11
	v_lshlrev_b32_e32 v6, s11, v0
	v_add_u32_e32 v6, v6, v1
	s_lshl_b32 s29, s18, 5
	s_lshl_b32 s29, s29, s13
	s_add_u32 s29, s29, s17
	s_add_u32 s29, s29, s14
	s_lshl_b32 s29, s29, 1
	s_add_u32 s22, s20, s29
	s_addc_u32 s23, s21, 0
	s_lshl_b32 s24, 16, s13
	s_add_i32 s29, s13, 1
	v_lshlrev_b32_e32 v8, s29, v2
	v_add_u32_e32 v8, v8, v3
	s_waitcnt lgkmcnt(0)
; #define LAS __attribute__((address_space(3)))
; __device__ __forceinline__ unsigned pk2(float lo, float hi) { return pg8::cvt_pk_bf16(lo, hi); }
; template <int KIND> __device__ __forceinline__ void tr_item(const float* __restrict__ W, int K, int Nsrc, const float* __restrict__ gk, bf16_t* WT, LAS float* scr, int item, int nblk, int lane) {
;     ...
;     for (int i = 0; i < 32; ++i) { const int kk = 2 * i + (lane >> 5); float v = 0.f; if (src >= 0) v = __builtin_nontemporal_load(&W[(size_t)(k0 + kk) * Nsrc + src]); if (gk) v *= gk[k0 + kk]; scr[kk * 33 + (lane & 31)] = v; }
;     asm volatile("s_waitcnt lgkmcnt(0)" ::: "memory");
;     const int c = lane & 7;
; #pragma unroll
;     for (int j = 0; j < 4; ++j) { const int n = (lane >> 3) + 8 * j; const LAS float* s = scr + (8 * c) * 33 + n;
;         u32x4 o; o.x = pk2(s[0 * 33], s[1 * 33]); o.y = pk2(s[2 * 33], s[3 * 33]); o.z = pk2(s[4 * 33], s[5 * 33]); o.w = pk2(s[6 * 33], s[7 * 33]);
;         *(u32x4*)(WT + (size_t)(n0 + n) * K + k0 + 8 * c) = o; }
	s_add_u32 s8, s6, s19
	s_addc_u32 s9, s7, 0
	global_load_dword v32, v6, s[8:9] nt
	s_add_u32 s8, s8, s10
	s_addc_u32 s9, s9, 0
	global_load_dword v33, v6, s[8:9] nt
	s_add_u32 s8, s8, s10
	s_addc_u32 s9, s9, 0
	global_load_dword v34, v6, s[8:9] nt
	s_add_u32 s8, s8, s10
	s_addc_u32 s9, s9, 0
	global_load_dword v35, v6, s[8:9] nt
	s_add_u32 s8, s8, s10
	s_addc_u32 s9, s9, 0
	global_load_dword v36, v6, s[8:9] nt
	s_add_u32 s8, s8, s10
	s_addc_u32 s9, s9, 0
	global_load_dword v37, v6, s[8:9] nt
	s_add_u32 s8, s8, s10
	s_addc_u32 s9, s9, 0
	global_load_dword v38, v6, s[8:9] nt
	s_add_u32 s8, s8, s10
	s_addc_u32 s9, s9, 0
	global_load_dword v39, v6, s[8:9] nt
	s_add_u32 s8, s8, s10
	s_addc_u32 s9, s9, 0
	global_load_dword v40, v6, s[8:9] nt
	s_add_u32 s8, s8, s10
	s_addc_u32 s9, s9, 0
	global_load_dword v41, v6, s[8:9] nt
	s_add_u32 s8, s8, s10
	s_addc_u32 s9, s9, 0
	global_load_dword v42, v6, s[8:9] nt
	s_add_u32 s8, s8, s10
	s_addc_u32 s9, s9, 0
	global_load_dword v43, v6, s[8:9] nt
	s_add_u32 s8, s8, s10
	s_addc_u32 s9, s9, 0
	global_load_dword v44, v6, s[8:9] nt
	s_add_u32 s8, s8, s10
	s_addc_u32 s9, s9, 0
	global_load_dword v45, v6, s[8:9] nt
	s_add_u32 s8, s8, s10
	s_addc_u32 s9, s9, 0
	global_load_dword v46, v6, s[8:9] nt
	s_add_u32 s8, s8, s10
	s_addc_u32 s9, s9, 0
	global_load_dword v47, v6, s[8:9] nt
	s_add_u32 s8, s8, s10
	s_addc_u32 s9, s9, 0
	global_load_dword v48, v6, s[8:9] nt
	s_add_u32 s8, s8, s10
	s_addc_u32 s9, s9, 0
	global_load_dword v49, v6, s[8:9] nt
	s_add_u32 s8, s8, s10
	s_addc_u32 s9, s9, 0
	global_load_dword v50, v6, s[8:9] nt
	s_add_u32 s8, s8, s10
	s_addc_u32 s9, s9, 0
	global_load_dword v51, v6, s[8:9] nt
	s_add_u32 s8, s8, s10
	s_addc_u32 s9, s9, 0
	global_load_dword v52, v6, s[8:9] nt
	s_add_u32 s8, s8, s10
	s_addc_u32 s9, s9, 0
	global_load_dword v53, v6, s[8:9] nt
	s_add_u32 s8, s8, s10
	s_addc_u32 s9, s9, 0
	global_load_dword v54, v6, s[8:9] nt
	s_add_u32 s8, s8, s10
	s_addc_u32 s9, s9, 0
	global_load_dword v55, v6, s[8:9] nt
	s_add_u32 s8, s8, s10
	s_addc_u32 s9, s9, 0
	global_load_dword v56, v6, s[8:9] nt
	s_add_u32 s8, s8, s10
	s_addc_u32 s9, s9, 0
	global_load_dword v57, v6, s[8:9] nt
	s_add_u32 s8, s8, s10
	s_addc_u32 s9, s9, 0
	global_load_dword v58, v6, s[8:9] nt
	s_add_u32 s8, s8, s10
	s_addc_u32 s9, s9, 0
	global_load_dword v59, v6, s[8:9] nt
	s_add_u32 s8, s8, s10
	s_addc_u32 s9, s9, 0
	global_load_dword v60, v6, s[8:9] nt
	s_add_u32 s8, s8, s10
	s_addc_u32 s9, s9, 0
	global_load_dword v61, v6, s[8:9] nt
	s_add_u32 s8, s8, s10
	s_addc_u32 s9, s9, 0
	global_load_dword v62, v6, s[8:9] nt
	s_add_u32 s8, s8, s10
	s_addc_u32 s9, s9, 0
	global_load_dword v63, v6, s[8:9] nt
	s_mov_b64 s[30:31], s[26:27]
	s_waitcnt vmcnt(63)
	ds_write_b32 v4, v64
	s_waitcnt vmcnt(63)
	ds_write_b32 v4, v65 offset:264
	s_waitcnt vmcnt(63)
	ds_write_b32 v4, v66 offset:528
	s_waitcnt vmcnt(63)
	ds_write_b32 v4, v67 offset:792
	s_waitcnt vmcnt(63)
	ds_write_b32 v4, v68 offset:1056
	s_waitcnt vmcnt(62)
	ds_write_b32 v4, v69 offset:1320
	s_waitcnt vmcnt(61)
	ds_write_b32 v4, v70 offset:1584
	s_waitcnt vmcnt(60)
	ds_write_b32 v4, v71 offset:1848
	s_waitcnt vmcnt(59)
	ds_write_b32 v4, v72 offset:2112
	s_waitcnt vmcnt(58)
	ds_write_b32 v4, v73 offset:2376
	s_waitcnt vmcnt(57)
	ds_write_b32 v4, v74 offset:2640
	s_waitcnt vmcnt(56)
	ds_write_b32 v4, v75 offset:2904
	s_waitcnt vmcnt(55)
	ds_write_b32 v4, v76 offset:3168
	s_waitcnt vmcnt(54)
	ds_write_b32 v4, v77 offset:3432
	s_waitcnt vmcnt(53)
	ds_write_b32 v4, v78 offset:3696
	s_waitcnt vmcnt(52)
	ds_write_b32 v4, v79 offset:3960
	s_waitcnt vmcnt(51)
	ds_write_b32 v4, v80 offset:4224
	s_waitcnt vmcnt(50)
	ds_write_b32 v4, v81 offset:4488
	s_waitcnt vmcnt(49)
	ds_write_b32 v4, v82 offset:4752
	s_waitcnt vmcnt(48)
	ds_write_b32 v4, v83 offset:5016
	s_waitcnt vmcnt(47)
	ds_write_b32 v4, v84 offset:5280
	s_waitcnt vmcnt(46)
	ds_write_b32 v4, v85 offset:5544
	s_waitcnt vmcnt(45)
	ds_write_b32 v4, v86 offset:5808
	s_waitcnt vmcnt(44)
	ds_write_b32 v4, v87 offset:6072
	s_waitcnt vmcnt(43)
	ds_write_b32 v4, v88 offset:6336
	s_waitcnt vmcnt(42)
	ds_write_b32 v4, v89 offset:6600
	s_waitcnt vmcnt(41)
	ds_write_b32 v4, v90 offset:6864
	s_waitcnt vmcnt(40)
	ds_write_b32 v4, v91 offset:7128
	s_waitcnt vmcnt(39)
	ds_write_b32 v4, v92 offset:7392
	s_waitcnt vmcnt(38)
	ds_write_b32 v4, v93 offset:7656
	s_waitcnt vmcnt(37)
	ds_write_b32 v4, v94 offset:7920
	s_waitcnt vmcnt(36)
	ds_write_b32 v4, v95 offset:8184
	s_waitcnt lgkmcnt(0)
	ds_read2_b32 v[96:97], v5 offset0:0 offset1:8
	ds_read2_b32 v[98:99], v5 offset0:16 offset1:24
	ds_read2_b32 v[100:101], v5 offset0:33 offset1:41
	ds_read2_b32 v[102:103], v5 offset0:49 offset1:57
	ds_read2_b32 v[104:105], v5 offset0:66 offset1:74
	ds_read2_b32 v[106:107], v5 offset0:82 offset1:90
	ds_read2_b32 v[108:109], v5 offset0:99 offset1:107
	ds_read2_b32 v[110:111], v5 offset0:115 offset1:123
	ds_read2_b32 v[112:113], v5 offset0:132 offset1:140
	ds_read2_b32 v[114:115], v5 offset0:148 offset1:156
	ds_read2_b32 v[116:117], v5 offset0:165 offset1:173
	ds_read2_b32 v[118:119], v5 offset0:181 offset1:189
	ds_read2_b32 v[120:121], v5 offset0:198 offset1:206
	ds_read2_b32 v[122:123], v5 offset0:214 offset1:222
	ds_read2_b32 v[124:125], v5 offset0:231 offset1:239
	ds_read2_b32 v[126:127], v5 offset0:247 offset1:255
	s_waitcnt lgkmcnt(0)
	v_cvt_pk_bf16_f32 v12, v96, v100
	v_cvt_pk_bf16_f32 v13, v104, v108
	v_cvt_pk_bf16_f32 v14, v112, v116
	v_cvt_pk_bf16_f32 v15, v120, v124
	global_store_dwordx4 v9, v[12:15], s[30:31]
	s_add_u32 s30, s30, s28
	s_addc_u32 s31, s31, 0
	v_cvt_pk_bf16_f32 v16, v97, v101
	v_cvt_pk_bf16_f32 v17, v105, v109
	v_cvt_pk_bf16_f32 v18, v113, v117
	v_cvt_pk_bf16_f32 v19, v121, v125
	global_store_dwordx4 v9, v[16:19], s[30:31]
	s_add_u32 s30, s30, s28
	s_addc_u32 s31, s31, 0
	v_cvt_pk_bf16_f32 v12, v98, v102
	v_cvt_pk_bf16_f32 v13, v106, v110
	v_cvt_pk_bf16_f32 v14, v114, v118
	v_cvt_pk_bf16_f32 v15, v122, v126
	global_store_dwordx4 v9, v[12:15], s[30:31]
	s_add_u32 s30, s30, s28
	s_addc_u32 s31, s31, 0
	v_cvt_pk_bf16_f32 v16, v99, v103
	v_cvt_pk_bf16_f32 v17, v107, v111
	v_cvt_pk_bf16_f32 v18, v115, v119
	v_cvt_pk_bf16_f32 v19, v123, v127
	global_store_dwordx4 v9, v[16:19], s[30:31]
	s_mov_b32 s4, s5
	s_add_i32 s5, s4, s82
	s_cmpk_gt_i32 s5, 0x547f
	s_cbranch_scc1 .Lp0g_tail_a
; #define LAS __attribute__((address_space(3)))
; #define INP(i) ((const float*)(const GAS float*)KARG(8 * (i)))
; template <int KIND> __device__ __forceinline__ void tr_item(const float* __restrict__ W, int K, int Nsrc, const float* __restrict__ gk, bf16_t* WT, LAS float* scr, int item, int nblk, int lane) {
;     const int kb = item / nblk, nb = item - kb * nblk, k0 = 64 * kb, n0 = 32 * nb;
;     const int src = srcmap<KIND>(n0 + (lane & 31));
; #pragma unroll 8
;     for (int i = 0; i < 32; ++i) { const int kk = 2 * i + (lane >> 5); float v = 0.f; if (src >= 0) v = __builtin_nontemporal_load(&W[(size_t)(k0 + kk) * Nsrc + src]); if (gk) v *= gk[k0 + kk]; scr[kk * 33 + (lane & 31)] = v; }
; __global__ void __launch_bounds__(512, 2) fwd(Params P) {
;     ...
;             if (r < I3) { tr_item<0>(INP(9), 1024, 2048, nullptr, wb + OFF_WSBO, scr, r, 2048 / 32, lane); continue; } r -= I3;
;             if (r < I4) { tr_item<0>(INP(10), 1024, 2048, nullptr, wb + OFF_WMLAO, scr, r, 2048 / 32, lane); continue; } r -= I4;
;             if (r < I5) { tr_item<0>(INP(11), 2048, 2048, nullptr, wb + OFF_WOUT, scr, r, 2048 / 32, lane); continue; } r -= I5;
;             if (r < I6) { tr_item<0>(INP(14), 2048, 8192, nullptr, wb + OFF_WUP, scr, r, 8192 / 32, lane); continue; } r -= I6;
;             if (r < I7) { tr_item<0>(INP(15), 8192, 2048, nullptr, wb + OFF_WDOWN, scr, r, 2048 / 32, lane); continue; } r -= I7;
;             if (r < I8) { tr_item<0>(INP(17), 256, 2048, nullptr, wb + OFF_WPLE, scr, r, 2048 / 32, lane); continue; } r -= I8;
;             tr_item<0>(INP(19), 2048, 2048, nullptr, wb + OFF_WPG, scr, r, 2048 / 32, lane);
	s_mov_b32 s16, 0x7580
	s_movk_i32 s15, 0x98
	s_mov_b32 s11, 13
	s_mov_b32 s12, 6
	s_mov_b32 s13, 11
	s_mov_b32 s14, 61603840
	s_cmpk_lt_u32 s5, 0x7580
	s_cselect_b32 s16, 0x7480, s16
	s_cselect_b32 s15, 0x88, s15
	s_cselect_b32 s11, 13, s11
	s_cselect_b32 s12, 6, s12
	s_cselect_b32 s13, 8, s13
	s_cselect_b32 s14, 61079552, s14
	s_cmpk_lt_u32 s5, 0x7480
	s_cselect_b32 s16, 0x5480, s16
	s_cselect_b32 s15, 0x78, s15
	s_cselect_b32 s11, 13, s11
	s_cselect_b32 s12, 6, s12
	s_cselect_b32 s13, 13, s13
	s_cselect_b32 s14, 44302336, s14
	s_cmpk_lt_u32 s5, 0x5480
	s_cselect_b32 s16, 0x3480, s16
	s_cselect_b32 s15, 0x70, s15
	s_cselect_b32 s11, 15, s11
	s_cselect_b32 s12, 8, s12
	s_cselect_b32 s13, 11, s13
	s_cselect_b32 s14, 27525120, s14
	s_cmpk_lt_u32 s5, 0x3480
	s_cselect_b32 s16, 0x2c80, s16
	s_cselect_b32 s15, 0x58, s15
	s_cselect_b32 s11, 13, s11
	s_cselect_b32 s12, 6, s12
	s_cselect_b32 s13, 11, s13
	s_cselect_b32 s14, 23330816, s14
	s_cmpk_lt_u32 s5, 0x2c80
	s_cselect_b32 s16, 0x2880, s16
	s_cselect_b32 s15, 0x50, s15
	s_cselect_b32 s11, 13, s11
	s_cselect_b32 s12, 6, s12
	s_cselect_b32 s13, 10, s13
	s_cselect_b32 s14, 21233664, s14
	s_cmpk_lt_u32 s5, 0x2880
	s_cselect_b32 s16, 0x2480, s16
	s_cselect_b32 s15, 0x48, s15
	s_cselect_b32 s11, 13, s11
	s_cselect_b32 s12, 6, s12
	s_cselect_b32 s13, 10, s13
	s_cselect_b32 s14, 19136512, s14
	s_load_dwordx2 s[6:7], s[0:1], s15
	s_sub_i32 s16, s5, s16
	s_lshl_b32 s19, 1, s12
	s_sub_i32 s19, s19, 1
	s_and_b32 s18, s16, s19
	s_lshr_b32 s17, s16, s12
	s_lshl_b32 s17, s17, 6
	s_lshl_b32 s19, s17, s11
	s_lshl_b32 s29, s18, 7
	s_add_u32 s19, s19, s29
	s_lshl_b32 s10, 2, s11
	v_lshlrev_b32_e32 v6, s11, v0
	v_add_u32_e32 v6, v6, v1
	s_lshl_b32 s29, s18, 5
	s_lshl_b32 s29, s29, s13
	s_add_u32 s29, s29, s17
	s_add_u32 s29, s29, s14
	s_lshl_b32 s29, s29, 1
	s_add_u32 s26, s20, s29
	s_addc_u32 s27, s21, 0
	s_lshl_b32 s28, 16, s13
	s_add_i32 s29, s13, 1
	v_lshlrev_b32_e32 v9, s29, v2
	v_add_u32_e32 v9, v9, v3
	s_waitcnt lgkmcnt(0)
	s_add_u32 s8, s6, s19
	s_addc_u32 s9, s7, 0
	global_load_dword v64, v6, s[8:9] nt
	s_add_u32 s8, s8, s10
	s_addc_u32 s9, s9, 0
	global_load_dword v65, v6, s[8:9] nt
	s_add_u32 s8, s8, s10
	s_addc_u32 s9, s9, 0
	global_load_dword v66, v6, s[8:9] nt
	s_add_u32 s8, s8, s10
	s_addc_u32 s9, s9, 0
	global_load_dword v67, v6, s[8:9] nt
	s_add_u32 s8, s8, s10
	s_addc_u32 s9, s9, 0
	global_load_dword v68, v6, s[8:9] nt
	s_add_u32 s8, s8, s10
	s_addc_u32 s9, s9, 0
	global_load_dword v69, v6, s[8:9] nt
	s_add_u32 s8, s8, s10
	s_addc_u32 s9, s9, 0
	global_load_dword v70, v6, s[8:9] nt
	s_add_u32 s8, s8, s10
	s_addc_u32 s9, s9, 0
	global_load_dword v71, v6, s[8:9] nt
	s_add_u32 s8, s8, s10
	s_addc_u32 s9, s9, 0
	global_load_dword v72, v6, s[8:9] nt
	s_add_u32 s8, s8, s10
	s_addc_u32 s9, s9, 0
	global_load_dword v73, v6, s[8:9] nt
	s_add_u32 s8, s8, s10
	s_addc_u32 s9, s9, 0
	global_load_dword v74, v6, s[8:9] nt
	s_add_u32 s8, s8, s10
	s_addc_u32 s9, s9, 0
	global_load_dword v75, v6, s[8:9] nt
	s_add_u32 s8, s8, s10
	s_addc_u32 s9, s9, 0
	global_load_dword v76, v6, s[8:9] nt
	s_add_u32 s8, s8, s10
	s_addc_u32 s9, s9, 0
	global_load_dword v77, v6, s[8:9] nt
	s_add_u32 s8, s8, s10
	s_addc_u32 s9, s9, 0
	global_load_dword v78, v6, s[8:9] nt
	s_add_u32 s8, s8, s10
	s_addc_u32 s9, s9, 0
	global_load_dword v79, v6, s[8:9] nt
	s_add_u32 s8, s8, s10
	s_addc_u32 s9, s9, 0
	global_load_dword v80, v6, s[8:9] nt
	s_add_u32 s8, s8, s10
	s_addc_u32 s9, s9, 0
	global_load_dword v81, v6, s[8:9] nt
	s_add_u32 s8, s8, s10
	s_addc_u32 s9, s9, 0
	global_load_dword v82, v6, s[8:9] nt
	s_add_u32 s8, s8, s10
	s_addc_u32 s9, s9, 0
	global_load_dword v83, v6, s[8:9] nt
	s_add_u32 s8, s8, s10
	s_addc_u32 s9, s9, 0
	global_load_dword v84, v6, s[8:9] nt
	s_add_u32 s8, s8, s10
	s_addc_u32 s9, s9, 0
	global_load_dword v85, v6, s[8:9] nt
	s_add_u32 s8, s8, s10
	s_addc_u32 s9, s9, 0
	global_load_dword v86, v6, s[8:9] nt
	s_add_u32 s8, s8, s10
	s_addc_u32 s9, s9, 0
	global_load_dword v87, v6, s[8:9] nt
	s_add_u32 s8, s8, s10
	s_addc_u32 s9, s9, 0
	global_load_dword v88, v6, s[8:9] nt
	s_add_u32 s8, s8, s10
	s_addc_u32 s9, s9, 0
	global_load_dword v89, v6, s[8:9] nt
	s_add_u32 s8, s8, s10
	s_addc_u32 s9, s9, 0
	global_load_dword v90, v6, s[8:9] nt
	s_add_u32 s8, s8, s10
	s_addc_u32 s9, s9, 0
	global_load_dword v91, v6, s[8:9] nt
	s_add_u32 s8, s8, s10
	s_addc_u32 s9, s9, 0
	global_load_dword v92, v6, s[8:9] nt
	s_add_u32 s8, s8, s10
	s_addc_u32 s9, s9, 0
	global_load_dword v93, v6, s[8:9] nt
	s_add_u32 s8, s8, s10
	s_addc_u32 s9, s9, 0
	global_load_dword v94, v6, s[8:9] nt
	s_add_u32 s8, s8, s10
	s_addc_u32 s9, s9, 0
	global_load_dword v95, v6, s[8:9] nt
	s_mov_b64 s[30:31], s[22:23]
	s_waitcnt vmcnt(63)
; #define LAS __attribute__((address_space(3)))
; __device__ __forceinline__ unsigned pk2(float lo, float hi) { return pg8::cvt_pk_bf16(lo, hi); }
; template <int KIND> __device__ __forceinline__ void tr_item(const float* __restrict__ W, int K, int Nsrc, const float* __restrict__ gk, bf16_t* WT, LAS float* scr, int item, int nblk, int lane) {
;     ...
;     for (int i = 0; i < 32; ++i) { const int kk = 2 * i + (lane >> 5); float v = 0.f; if (src >= 0) v = __builtin_nontemporal_load(&W[(size_t)(k0 + kk) * Nsrc + src]); if (gk) v *= gk[k0 + kk]; scr[kk * 33 + (lane & 31)] = v; }
;     asm volatile("s_waitcnt lgkmcnt(0)" ::: "memory");
;     const int c = lane & 7;
; #pragma unroll
;     for (int j = 0; j < 4; ++j) { const int n = (lane >> 3) + 8 * j; const LAS float* s = scr + (8 * c) * 33 + n;
;         u32x4 o; o.x = pk2(s[0 * 33], s[1 * 33]); o.y = pk2(s[2 * 33], s[3 * 33]); o.z = pk2(s[4 * 33], s[5 * 33]); o.w = pk2(s[6 * 33], s[7 * 33]);
;         *(u32x4*)(WT + (size_t)(n0 + n) * K + k0 + 8 * c) = o; }
	ds_write_b32 v4, v32
	s_waitcnt vmcnt(63)
	ds_write_b32 v4, v33 offset:264
	s_waitcnt vmcnt(63)
	ds_write_b32 v4, v34 offset:528
	s_waitcnt vmcnt(63)
	ds_write_b32 v4, v35 offset:792
	s_waitcnt vmcnt(63)
	ds_write_b32 v4, v36 offset:1056
	s_waitcnt vmcnt(62)
	ds_write_b32 v4, v37 offset:1320
	s_waitcnt vmcnt(61)
	ds_write_b32 v4, v38 offset:1584
	s_waitcnt vmcnt(60)
	ds_write_b32 v4, v39 offset:1848
	s_waitcnt vmcnt(59)
	ds_write_b32 v4, v40 offset:2112
	s_waitcnt vmcnt(58)
	ds_write_b32 v4, v41 offset:2376
	s_waitcnt vmcnt(57)
	ds_write_b32 v4, v42 offset:2640
	s_waitcnt vmcnt(56)
	ds_write_b32 v4, v43 offset:2904
	s_waitcnt vmcnt(55)
	ds_write_b32 v4, v44 offset:3168
	s_waitcnt vmcnt(54)
	ds_write_b32 v4, v45 offset:3432
	s_waitcnt vmcnt(53)
	ds_write_b32 v4, v46 offset:3696
	s_waitcnt vmcnt(52)
	ds_write_b32 v4, v47 offset:3960
	s_waitcnt vmcnt(51)
	ds_write_b32 v4, v48 offset:4224
	s_waitcnt vmcnt(50)
	ds_write_b32 v4, v49 offset:4488
	s_waitcnt vmcnt(49)
	ds_write_b32 v4, v50 offset:4752
	s_waitcnt vmcnt(48)
	ds_write_b32 v4, v51 offset:5016
	s_waitcnt vmcnt(47)
	ds_write_b32 v4, v52 offset:5280
	s_waitcnt vmcnt(46)
	ds_write_b32 v4, v53 offset:5544
	s_waitcnt vmcnt(45)
	ds_write_b32 v4, v54 offset:5808
	s_waitcnt vmcnt(44)
	ds_write_b32 v4, v55 offset:6072
	s_waitcnt vmcnt(43)
	ds_write_b32 v4, v56 offset:6336
	s_waitcnt vmcnt(42)
	ds_write_b32 v4, v57 offset:6600
	s_waitcnt vmcnt(41)
	ds_write_b32 v4, v58 offset:6864
	s_waitcnt vmcnt(40)
	ds_write_b32 v4, v59 offset:7128
	s_waitcnt vmcnt(39)
	ds_write_b32 v4, v60 offset:7392
	s_waitcnt vmcnt(38)
	ds_write_b32 v4, v61 offset:7656
	s_waitcnt vmcnt(37)
	ds_write_b32 v4, v62 offset:7920
	s_waitcnt vmcnt(36)
	ds_write_b32 v4, v63 offset:8184
	s_waitcnt lgkmcnt(0)
	ds_read2_b32 v[96:97], v5 offset0:0 offset1:8
	ds_read2_b32 v[98:99], v5 offset0:16 offset1:24
	ds_read2_b32 v[100:101], v5 offset0:33 offset1:41
	ds_read2_b32 v[102:103], v5 offset0:49 offset1:57
	ds_read2_b32 v[104:105], v5 offset0:66 offset1:74
	ds_read2_b32 v[106:107], v5 offset0:82 offset1:90
	ds_read2_b32 v[108:109], v5 offset0:99 offset1:107
	ds_read2_b32 v[110:111], v5 offset0:115 offset1:123
	ds_read2_b32 v[112:113], v5 offset0:132 offset1:140
	ds_read2_b32 v[114:115], v5 offset0:148 offset1:156
	ds_read2_b32 v[116:117], v5 offset0:165 offset1:173
	ds_read2_b32 v[118:119], v5 offset0:181 offset1:189
	ds_read2_b32 v[120:121], v5 offset0:198 offset1:206
	ds_read2_b32 v[122:123], v5 offset0:214 offset1:222
	ds_read2_b32 v[124:125], v5 offset0:231 offset1:239
	ds_read2_b32 v[126:127], v5 offset0:247 offset1:255
	s_waitcnt lgkmcnt(0)
	v_cvt_pk_bf16_f32 v12, v96, v100
	v_cvt_pk_bf16_f32 v13, v104, v108
	v_cvt_pk_bf16_f32 v14, v112, v116
	v_cvt_pk_bf16_f32 v15, v120, v124
	global_store_dwordx4 v8, v[12:15], s[30:31]
	s_add_u32 s30, s30, s24
	s_addc_u32 s31, s31, 0
	v_cvt_pk_bf16_f32 v16, v97, v101
	v_cvt_pk_bf16_f32 v17, v105, v109
	v_cvt_pk_bf16_f32 v18, v113, v117
	v_cvt_pk_bf16_f32 v19, v121, v125
	global_store_dwordx4 v8, v[16:19], s[30:31]
	s_add_u32 s30, s30, s24
	s_addc_u32 s31, s31, 0
	v_cvt_pk_bf16_f32 v12, v98, v102
	v_cvt_pk_bf16_f32 v13, v106, v110
	v_cvt_pk_bf16_f32 v14, v114, v118
	v_cvt_pk_bf16_f32 v15, v122, v126
	global_store_dwordx4 v8, v[12:15], s[30:31]
	s_add_u32 s30, s30, s24
	s_addc_u32 s31, s31, 0
	v_cvt_pk_bf16_f32 v16, v99, v103
	v_cvt_pk_bf16_f32 v17, v107, v111
	v_cvt_pk_bf16_f32 v18, v115, v119
	v_cvt_pk_bf16_f32 v19, v123, v127
	global_store_dwordx4 v8, v[16:19], s[30:31]
	s_mov_b32 s4, s5
	s_branch .Lp0g_loop

; #define LAS __attribute__((address_space(3)))
; #define INP(i) ((const float*)(const GAS float*)KARG(8 * (i)))
; template <int KIND> __device__ __forceinline__ void tr_item(const float* __restrict__ W, int K, int Nsrc, const float* __restrict__ gk, bf16_t* WT, LAS float* scr, int item, int nblk, int lane) {
;     const int kb = item / nblk, nb = item - kb * nblk, k0 = 64 * kb, n0 = 32 * nb;
;     const int src = srcmap<KIND>(n0 + (lane & 31));
; #pragma unroll 8
;     for (int i = 0; i < 32; ++i) { const int kk = 2 * i + (lane >> 5); float v = 0.f; if (src >= 0) v = __builtin_nontemporal_load(&W[(size_t)(k0 + kk) * Nsrc + src]); if (gk) v *= gk[k0 + kk]; scr[kk * 33 + (lane & 31)] = v; }
; __global__ void __launch_bounds__(512, 2) fwd(Params P) {
;     ...
;         for (int it = gw; it < NITEMS; it += NGW) {
;             int r = it;
;             if (r < I0) { tr_item<1>(INP(4), 2048, 8256, nullptr, wb + OFF_WIN, scr, r, NIN / 32, lane); continue; } r -= I0;
;             if (r < I1) { tr_item<2>(INP(7), 512, 1536, INP(5), wb + OFF_WQ, scr, r, 1536 / 32, lane); continue; } r -= I1;
;             if (r < I2) { tr_item<0>(INP(8), 512, 2048, INP(6), wb + OFF_WKV, scr, r, 2048 / 32, lane); continue; } r -= I2;
;             if (r < I3) { tr_item<0>(INP(9), 1024, 2048, nullptr, wb + OFF_WSBO, scr, r, 2048 / 32, lane); continue; } r -= I3;
;             if (r < I4) { tr_item<0>(INP(10), 1024, 2048, nullptr, wb + OFF_WMLAO, scr, r, 2048 / 32, lane); continue; } r -= I4;
;             if (r < I5) { tr_item<0>(INP(11), 2048, 2048, nullptr, wb + OFF_WOUT, scr, r, 2048 / 32, lane); continue; } r -= I5;
;             if (r < I6) { tr_item<0>(INP(14), 2048, 8192, nullptr, wb + OFF_WUP, scr, r, 8192 / 32, lane); continue; } r -= I6;
;             if (r < I7) { tr_item<0>(INP(15), 8192, 2048, nullptr, wb + OFF_WDOWN, scr, r, 2048 / 32, lane); continue; } r -= I7;
;             if (r < I8) { tr_item<0>(INP(17), 256, 2048, nullptr, wb + OFF_WPLE, scr, r, 2048 / 32, lane); continue; } r -= I8;
;             tr_item<0>(INP(19), 2048, 2048, nullptr, wb + OFF_WPG, scr, r, 2048 / 32, lane);
.LBB0_503:
	s_waitcnt vmcnt(0)
	s_cmp_lt_u32 s84, 0x80
	s_cbranch_scc1 .Lp1t_skip
	s_barrier
.Lp1t_entry:
	v_readfirstlane_b32 s32, v178
	s_load_dwordx2 s[20:21], s[0:1], 0xa8
	v_lshrrev_b32_e32 v0, 5, v179
	v_and_b32_e32 v1, 31, v179
	v_lshrrev_b32_e32 v2, 3, v179
	v_and_b32_e32 v3, 7, v179
	s_lshr_b32 s32, s32, 6
	s_lshl_b32 s32, s32, 14
	v_lshlrev_b32_e32 v1, 2, v1
	v_mul_u32_u24_e32 v4, 0x84, v0
	v_mul_u32_u24_e32 v5, 0x420, v3
	v_add3_u32 v4, v4, v1, s32
	v_lshl_add_u32 v5, v2, 2, v5
	v_add_u32_e32 v5, s32, v5
	v_lshlrev_b32_e32 v3, 4, v3
	s_sub_i32 s4, s84, 0x80
	s_lshl_b32 s4, s4, 3
	s_lshr_b32 s5, s32, 14
	s_add_i32 s4, s4, s5
	s_add_i32 s4, s4, 0x5480
	s_waitcnt lgkmcnt(0)
	s_add_u32 s20, s20, 0x100000
	s_addc_u32 s21, s21, 0
	s_mov_b32 s16, 0x7580
	s_movk_i32 s15, 0x98
	s_mov_b32 s11, 13
	s_mov_b32 s12, 6
	s_mov_b32 s13, 11
	s_mov_b32 s14, 61603840
	s_cmpk_lt_u32 s4, 0x7580
	s_cselect_b32 s16, 0x7480, s16
	s_cselect_b32 s15, 0x88, s15
	s_cselect_b32 s11, 13, s11
	s_cselect_b32 s12, 6, s12
	s_cselect_b32 s13, 8, s13
	s_cselect_b32 s14, 61079552, s14
	s_cmpk_lt_u32 s4, 0x7480
	s_cselect_b32 s16, 0x5480, s16
	s_cselect_b32 s15, 0x78, s15
	s_cselect_b32 s11, 13, s11
	s_cselect_b32 s12, 6, s12
	s_cselect_b32 s13, 13, s13
	s_cselect_b32 s14, 44302336, s14
	s_cmpk_lt_u32 s4, 0x5480
	s_cselect_b32 s16, 0x3480, s16
	s_cselect_b32 s15, 0x70, s15
	s_cselect_b32 s11, 15, s11
	s_cselect_b32 s12, 8, s12
	s_cselect_b32 s13, 11, s13
	s_cselect_b32 s14, 27525120, s14
	s_cmpk_lt_u32 s4, 0x3480
	s_cselect_b32 s16, 0x2c80, s16
	s_cselect_b32 s15, 0x58, s15
	s_cselect_b32 s11, 13, s11
	s_cselect_b32 s12, 6, s12
	s_cselect_b32 s13, 11, s13
	s_cselect_b32 s14, 23330816, s14
	s_cmpk_lt_u32 s4, 0x2c80
	s_cselect_b32 s16, 0x2880, s16
	s_cselect_b32 s15, 0x50, s15
	s_cselect_b32 s11, 13, s11
	s_cselect_b32 s12, 6, s12
	s_cselect_b32 s13, 10, s13
	s_cselect_b32 s14, 21233664, s14
	s_cmpk_lt_u32 s4, 0x2880
	s_cselect_b32 s16, 0x2480, s16
	s_cselect_b32 s15, 0x48, s15
	s_cselect_b32 s11, 13, s11
	s_cselect_b32 s12, 6, s12
	s_cselect_b32 s13, 10, s13
	s_cselect_b32 s14, 19136512, s14
	s_load_dwordx2 s[6:7], s[0:1], s15
	s_sub_i32 s16, s4, s16
	s_lshl_b32 s19, 1, s12
	s_sub_i32 s19, s19, 1
	s_and_b32 s18, s16, s19
	s_lshr_b32 s17, s16, s12
	s_lshl_b32 s17, s17, 6
	s_lshl_b32 s19, s17, s11
	s_lshl_b32 s29, s18, 7
	s_add_u32 s19, s19, s29
	s_lshl_b32 s10, 2, s11
	v_lshlrev_b32_e32 v6, s11, v0
	v_add_u32_e32 v6, v6, v1
	s_lshl_b32 s29, s18, 5
	s_lshl_b32 s29, s29, s13
	s_add_u32 s29, s29, s17
	s_add_u32 s29, s29, s14
	s_lshl_b32 s29, s29, 1
	s_add_u32 s22, s20, s29
	s_addc_u32 s23, s21, 0
	s_lshl_b32 s24, 16, s13
	s_add_i32 s29, s13, 1
	v_lshlrev_b32_e32 v8, s29, v2
	v_add_u32_e32 v8, v8, v3
	s_waitcnt lgkmcnt(0)
	s_add_u32 s8, s6, s19
	s_addc_u32 s9, s7, 0
	global_load_dword v32, v6, s[8:9] nt
	s_add_u32 s8, s8, s10
	s_addc_u32 s9, s9, 0
	global_load_dword v33, v6, s[8:9] nt
	s_add_u32 s8, s8, s10
	s_addc_u32 s9, s9, 0
	global_load_dword v34, v6, s[8:9] nt
	s_add_u32 s8, s8, s10
	s_addc_u32 s9, s9, 0
	global_load_dword v35, v6, s[8:9] nt
	s_add_u32 s8, s8, s10
	s_addc_u32 s9, s9, 0
	global_load_dword v36, v6, s[8:9] nt
	s_add_u32 s8, s8, s10
	s_addc_u32 s9, s9, 0
	global_load_dword v37, v6, s[8:9] nt
	s_add_u32 s8, s8, s10
	s_addc_u32 s9, s9, 0
	global_load_dword v38, v6, s[8:9] nt
	s_add_u32 s8, s8, s10
	s_addc_u32 s9, s9, 0
	global_load_dword v39, v6, s[8:9] nt
	s_add_u32 s8, s8, s10
	s_addc_u32 s9, s9, 0
	global_load_dword v40, v6, s[8:9] nt
	s_add_u32 s8, s8, s10
	s_addc_u32 s9, s9, 0
	global_load_dword v41, v6, s[8:9] nt
	s_add_u32 s8, s8, s10
	s_addc_u32 s9, s9, 0
	global_load_dword v42, v6, s[8:9] nt
	s_add_u32 s8, s8, s10
	s_addc_u32 s9, s9, 0
	global_load_dword v43, v6, s[8:9] nt
	s_add_u32 s8, s8, s10
	s_addc_u32 s9, s9, 0
	global_load_dword v44, v6, s[8:9] nt
	s_add_u32 s8, s8, s10
	s_addc_u32 s9, s9, 0
	global_load_dword v45, v6, s[8:9] nt
	s_add_u32 s8, s8, s10
	s_addc_u32 s9, s9, 0
	global_load_dword v46, v6, s[8:9] nt
	s_add_u32 s8, s8, s10
	s_addc_u32 s9, s9, 0
	global_load_dword v47, v6, s[8:9] nt
	s_add_u32 s8, s8, s10
	s_addc_u32 s9, s9, 0
	global_load_dword v48, v6, s[8:9] nt
	s_add_u32 s8, s8, s10
	s_addc_u32 s9, s9, 0
	global_load_dword v49, v6, s[8:9] nt
	s_add_u32 s8, s8, s10
	s_addc_u32 s9, s9, 0
	global_load_dword v50, v6, s[8:9] nt
	s_add_u32 s8, s8, s10
	s_addc_u32 s9, s9, 0
	global_load_dword v51, v6, s[8:9] nt
	s_add_u32 s8, s8, s10
	s_addc_u32 s9, s9, 0
	global_load_dword v52, v6, s[8:9] nt
	s_add_u32 s8, s8, s10
	s_addc_u32 s9, s9, 0
	global_load_dword v53, v6, s[8:9] nt
	s_add_u32 s8, s8, s10
	s_addc_u32 s9, s9, 0
	global_load_dword v54, v6, s[8:9] nt
	s_add_u32 s8, s8, s10
	s_addc_u32 s9, s9, 0
	global_load_dword v55, v6, s[8:9] nt
	s_add_u32 s8, s8, s10
	s_addc_u32 s9, s9, 0
	global_load_dword v56, v6, s[8:9] nt
	s_add_u32 s8, s8, s10
	s_addc_u32 s9, s9, 0
	global_load_dword v57, v6, s[8:9] nt
	s_add_u32 s8, s8, s10
	s_addc_u32 s9, s9, 0
	global_load_dword v58, v6, s[8:9] nt
	s_add_u32 s8, s8, s10
	s_addc_u32 s9, s9, 0
	global_load_dword v59, v6, s[8:9] nt
	s_add_u32 s8, s8, s10
	s_addc_u32 s9, s9, 0
	global_load_dword v60, v6, s[8:9] nt
	s_add_u32 s8, s8, s10
	s_addc_u32 s9, s9, 0
	global_load_dword v61, v6, s[8:9] nt
	s_add_u32 s8, s8, s10
	s_addc_u32 s9, s9, 0
	global_load_dword v62, v6, s[8:9] nt
	s_add_u32 s8, s8, s10
	s_addc_u32 s9, s9, 0
	global_load_dword v63, v6, s[8:9] nt
	s_add_i32 s5, s4, 0x400
	s_cmpk_gt_i32 s5, 0x7d7f
	s_cbranch_scc1 .Lp1t_tail_a
; #define LAS __attribute__((address_space(3)))
; template <int KIND> __device__ __forceinline__ void tr_item(const float* __restrict__ W, int K, int Nsrc, const float* __restrict__ gk, bf16_t* WT, LAS float* scr, int item, int nblk, int lane) {
;     const int kb = item / nblk, nb = item - kb * nblk, k0 = 64 * kb, n0 = 32 * nb;
;     const int src = srcmap<KIND>(n0 + (lane & 31));
; #pragma unroll 8
;     for (int i = 0; i < 32; ++i) { const int kk = 2 * i + (lane >> 5); float v = 0.f; if (src >= 0) v = __builtin_nontemporal_load(&W[(size_t)(k0 + kk) * Nsrc + src]); if (gk) v *= gk[k0 + kk]; scr[kk * 33 + (lane & 31)] = v; }
;     asm volatile("s_waitcnt lgkmcnt(0)" ::: "memory");
;     const int c = lane & 7;
; #pragma unroll
;     for (int j = 0; j < 4; ++j) { const int n = (lane >> 3) + 8 * j; const LAS float* s = scr + (8 * c) * 33 + n;
	s_mov_b32 s16, 0x7580
	s_movk_i32 s15, 0x98
	s_mov_b32 s11, 13
	s_mov_b32 s12, 6
	s_mov_b32 s13, 11
	s_mov_b32 s14, 61603840
	s_cmpk_lt_u32 s5, 0x7580
	s_cselect_b32 s16, 0x7480, s16
	s_cselect_b32 s15, 0x88, s15
	s_cselect_b32 s11, 13, s11
	s_cselect_b32 s12, 6, s12
	s_cselect_b32 s13, 8, s13
	s_cselect_b32 s14, 61079552, s14
	s_cmpk_lt_u32 s5, 0x7480
	s_cselect_b32 s16, 0x5480, s16
	s_cselect_b32 s15, 0x78, s15
	s_cselect_b32 s11, 13, s11
	s_cselect_b32 s12, 6, s12
	s_cselect_b32 s13, 13, s13
	s_cselect_b32 s14, 44302336, s14
	s_cmpk_lt_u32 s5, 0x5480
	s_cselect_b32 s16, 0x3480, s16
	s_cselect_b32 s15, 0x70, s15
	s_cselect_b32 s11, 15, s11
	s_cselect_b32 s12, 8, s12
	s_cselect_b32 s13, 11, s13
	s_cselect_b32 s14, 27525120, s14
	s_cmpk_lt_u32 s5, 0x3480
	s_cselect_b32 s16, 0x2c80, s16
	s_cselect_b32 s15, 0x58, s15
	s_cselect_b32 s11, 13, s11
	s_cselect_b32 s12, 6, s12
	s_cselect_b32 s13, 11, s13
	s_cselect_b32 s14, 23330816, s14
	s_cmpk_lt_u32 s5, 0x2c80
	s_cselect_b32 s16, 0x2880, s16
	s_cselect_b32 s15, 0x50, s15
	s_cselect_b32 s11, 13, s11
	s_cselect_b32 s12, 6, s12
	s_cselect_b32 s13, 10, s13
	s_cselect_b32 s14, 21233664, s14
	s_cmpk_lt_u32 s5, 0x2880
	s_cselect_b32 s16, 0x2480, s16
	s_cselect_b32 s15, 0x48, s15
	s_cselect_b32 s11, 13, s11
	s_cselect_b32 s12, 6, s12
	s_cselect_b32 s13, 10, s13
	s_cselect_b32 s14, 19136512, s14
	s_load_dwordx2 s[6:7], s[0:1], s15
	s_sub_i32 s16, s5, s16
	s_lshl_b32 s19, 1, s12
	s_sub_i32 s19, s19, 1
	s_and_b32 s18, s16, s19
	s_lshr_b32 s17, s16, s12
	s_lshl_b32 s17, s17, 6
	s_lshl_b32 s19, s17, s11
	s_lshl_b32 s29, s18, 7
	s_add_u32 s19, s19, s29
	s_lshl_b32 s10, 2, s11
	v_lshlrev_b32_e32 v6, s11, v0
	v_add_u32_e32 v6, v6, v1
	s_lshl_b32 s29, s18, 5
	s_lshl_b32 s29, s29, s13
	s_add_u32 s29, s29, s17
	s_add_u32 s29, s29, s14
	s_lshl_b32 s29, s29, 1
	s_add_u32 s26, s20, s29
	s_addc_u32 s27, s21, 0
	s_lshl_b32 s28, 16, s13
	s_add_i32 s29, s13, 1
	v_lshlrev_b32_e32 v9, s29, v2
	v_add_u32_e32 v9, v9, v3
	s_waitcnt lgkmcnt(0)
	s_add_u32 s8, s6, s19
	s_addc_u32 s9, s7, 0
	global_load_dword v64, v6, s[8:9] nt
	s_add_u32 s8, s8, s10
	s_addc_u32 s9, s9, 0
	global_load_dword v65, v6, s[8:9] nt
	s_add_u32 s8, s8, s10
	s_addc_u32 s9, s9, 0
	global_load_dword v66, v6, s[8:9] nt
	s_add_u32 s8, s8, s10
	s_addc_u32 s9, s9, 0
	global_load_dword v67, v6, s[8:9] nt
	s_add_u32 s8, s8, s10
	s_addc_u32 s9, s9, 0
	global_load_dword v68, v6, s[8:9] nt
	s_add_u32 s8, s8, s10
	s_addc_u32 s9, s9, 0
	global_load_dword v69, v6, s[8:9] nt
	s_add_u32 s8, s8, s10
	s_addc_u32 s9, s9, 0
	global_load_dword v70, v6, s[8:9] nt
	s_add_u32 s8, s8, s10
	s_addc_u32 s9, s9, 0
	global_load_dword v71, v6, s[8:9] nt
	s_add_u32 s8, s8, s10
	s_addc_u32 s9, s9, 0
	global_load_dword v72, v6, s[8:9] nt
	s_add_u32 s8, s8, s10
	s_addc_u32 s9, s9, 0
	global_load_dword v73, v6, s[8:9] nt
	s_add_u32 s8, s8, s10
	s_addc_u32 s9, s9, 0
	global_load_dword v74, v6, s[8:9] nt
	s_add_u32 s8, s8, s10
	s_addc_u32 s9, s9, 0
	global_load_dword v75, v6, s[8:9] nt
	s_add_u32 s8, s8, s10
	s_addc_u32 s9, s9, 0
	global_load_dword v76, v6, s[8:9] nt
	s_add_u32 s8, s8, s10
	s_addc_u32 s9, s9, 0
	global_load_dword v77, v6, s[8:9] nt
	s_add_u32 s8, s8, s10
	s_addc_u32 s9, s9, 0
	global_load_dword v78, v6, s[8:9] nt
	s_add_u32 s8, s8, s10
	s_addc_u32 s9, s9, 0
	global_load_dword v79, v6, s[8:9] nt
	s_add_u32 s8, s8, s10
	s_addc_u32 s9, s9, 0
	global_load_dword v80, v6, s[8:9] nt
	s_add_u32 s8, s8, s10
	s_addc_u32 s9, s9, 0
	global_load_dword v81, v6, s[8:9] nt
	s_add_u32 s8, s8, s10
	s_addc_u32 s9, s9, 0
	global_load_dword v82, v6, s[8:9] nt
	s_add_u32 s8, s8, s10
	s_addc_u32 s9, s9, 0
	global_load_dword v83, v6, s[8:9] nt
	s_add_u32 s8, s8, s10
	s_addc_u32 s9, s9, 0
	global_load_dword v84, v6, s[8:9] nt
	s_add_u32 s8, s8, s10
	s_addc_u32 s9, s9, 0
	global_load_dword v85, v6, s[8:9] nt
	s_add_u32 s8, s8, s10
	s_addc_u32 s9, s9, 0
	global_load_dword v86, v6, s[8:9] nt
	s_add_u32 s8, s8, s10
	s_addc_u32 s9, s9, 0
	global_load_dword v87, v6, s[8:9] nt
	s_add_u32 s8, s8, s10
	s_addc_u32 s9, s9, 0
	global_load_dword v88, v6, s[8:9] nt
	s_add_u32 s8, s8, s10
	s_addc_u32 s9, s9, 0
	global_load_dword v89, v6, s[8:9] nt
	s_add_u32 s8, s8, s10
	s_addc_u32 s9, s9, 0
	global_load_dword v90, v6, s[8:9] nt
	s_add_u32 s8, s8, s10
	s_addc_u32 s9, s9, 0
	global_load_dword v91, v6, s[8:9] nt
	s_add_u32 s8, s8, s10
	s_addc_u32 s9, s9, 0
	global_load_dword v92, v6, s[8:9] nt
	s_add_u32 s8, s8, s10
	s_addc_u32 s9, s9, 0
	global_load_dword v93, v6, s[8:9] nt
	s_add_u32 s8, s8, s10
	s_addc_u32 s9, s9, 0
	global_load_dword v94, v6, s[8:9] nt
	s_add_u32 s8, s8, s10
	s_addc_u32 s9, s9, 0
	global_load_dword v95, v6, s[8:9] nt
	s_mov_b64 s[30:31], s[22:23]
	s_waitcnt vmcnt(63)
	ds_write_b32 v4, v32
	s_waitcnt vmcnt(62)
	ds_write_b32 v4, v33 offset:264
	s_waitcnt vmcnt(61)
	ds_write_b32 v4, v34 offset:528
	s_waitcnt vmcnt(60)
	ds_write_b32 v4, v35 offset:792
	s_waitcnt vmcnt(59)
	ds_write_b32 v4, v36 offset:1056
	s_waitcnt vmcnt(58)
	ds_write_b32 v4, v37 offset:1320
	s_waitcnt vmcnt(57)
	ds_write_b32 v4, v38 offset:1584
	s_waitcnt vmcnt(56)
	ds_write_b32 v4, v39 offset:1848
	s_waitcnt vmcnt(55)
	ds_write_b32 v4, v40 offset:2112
	s_waitcnt vmcnt(54)
	ds_write_b32 v4, v41 offset:2376
	s_waitcnt vmcnt(53)
	ds_write_b32 v4, v42 offset:2640
	s_waitcnt vmcnt(52)
	ds_write_b32 v4, v43 offset:2904
	s_waitcnt vmcnt(51)
	ds_write_b32 v4, v44 offset:3168
	s_waitcnt vmcnt(50)
	ds_write_b32 v4, v45 offset:3432
	s_waitcnt vmcnt(49)
	ds_write_b32 v4, v46 offset:3696
	s_waitcnt vmcnt(48)
	ds_write_b32 v4, v47 offset:3960
	s_waitcnt vmcnt(47)
	ds_write_b32 v4, v48 offset:4224
	s_waitcnt vmcnt(46)
; #define LAS __attribute__((address_space(3)))
; __device__ __forceinline__ unsigned pk2(float lo, float hi) { return pg8::cvt_pk_bf16(lo, hi); }
; template <int KIND> __device__ __forceinline__ void tr_item(const float* __restrict__ W, int K, int Nsrc, const float* __restrict__ gk, bf16_t* WT, LAS float* scr, int item, int nblk, int lane) {
;     ...
;     for (int i = 0; i < 32; ++i) { const int kk = 2 * i + (lane >> 5); float v = 0.f; if (src >= 0) v = __builtin_nontemporal_load(&W[(size_t)(k0 + kk) * Nsrc + src]); if (gk) v *= gk[k0 + kk]; scr[kk * 33 + (lane & 31)] = v; }
;     asm volatile("s_waitcnt lgkmcnt(0)" ::: "memory");
;     const int c = lane & 7;
; #pragma unroll
;     for (int j = 0; j < 4; ++j) { const int n = (lane >> 3) + 8 * j; const LAS float* s = scr + (8 * c) * 33 + n;
;         u32x4 o; o.x = pk2(s[0 * 33], s[1 * 33]); o.y = pk2(s[2 * 33], s[3 * 33]); o.z = pk2(s[4 * 33], s[5 * 33]); o.w = pk2(s[6 * 33], s[7 * 33]);
;         *(u32x4*)(WT + (size_t)(n0 + n) * K + k0 + 8 * c) = o; }
	ds_write_b32 v4, v49 offset:4488
	s_waitcnt vmcnt(45)
	ds_write_b32 v4, v50 offset:4752
	s_waitcnt vmcnt(44)
	ds_write_b32 v4, v51 offset:5016
	s_waitcnt vmcnt(43)
	ds_write_b32 v4, v52 offset:5280
	s_waitcnt vmcnt(42)
	ds_write_b32 v4, v53 offset:5544
	s_waitcnt vmcnt(41)
	ds_write_b32 v4, v54 offset:5808
	s_waitcnt vmcnt(40)
	ds_write_b32 v4, v55 offset:6072
	s_waitcnt vmcnt(39)
	ds_write_b32 v4, v56 offset:6336
	s_waitcnt vmcnt(38)
	ds_write_b32 v4, v57 offset:6600
	s_waitcnt vmcnt(37)
	ds_write_b32 v4, v58 offset:6864
	s_waitcnt vmcnt(36)
	ds_write_b32 v4, v59 offset:7128
	s_waitcnt vmcnt(35)
	ds_write_b32 v4, v60 offset:7392
	s_waitcnt vmcnt(34)
	ds_write_b32 v4, v61 offset:7656
	s_waitcnt vmcnt(33)
	ds_write_b32 v4, v62 offset:7920
	s_waitcnt vmcnt(32)
	ds_write_b32 v4, v63 offset:8184
	s_waitcnt lgkmcnt(0)
	ds_read2_b32 v[96:97], v5 offset0:0 offset1:8
	ds_read2_b32 v[98:99], v5 offset0:16 offset1:24
	ds_read2_b32 v[100:101], v5 offset0:33 offset1:41
	ds_read2_b32 v[102:103], v5 offset0:49 offset1:57
	ds_read2_b32 v[104:105], v5 offset0:66 offset1:74
	ds_read2_b32 v[106:107], v5 offset0:82 offset1:90
	ds_read2_b32 v[108:109], v5 offset0:99 offset1:107
	ds_read2_b32 v[110:111], v5 offset0:115 offset1:123
	ds_read2_b32 v[112:113], v5 offset0:132 offset1:140
	ds_read2_b32 v[114:115], v5 offset0:148 offset1:156
	ds_read2_b32 v[116:117], v5 offset0:165 offset1:173
	ds_read2_b32 v[118:119], v5 offset0:181 offset1:189
	ds_read2_b32 v[120:121], v5 offset0:198 offset1:206
	ds_read2_b32 v[122:123], v5 offset0:214 offset1:222
	ds_read2_b32 v[124:125], v5 offset0:231 offset1:239
	ds_read2_b32 v[126:127], v5 offset0:247 offset1:255
	s_waitcnt lgkmcnt(0)
	v_cvt_pk_bf16_f32 v12, v96, v100
	v_cvt_pk_bf16_f32 v13, v104, v108
	v_cvt_pk_bf16_f32 v14, v112, v116
	v_cvt_pk_bf16_f32 v15, v120, v124
	global_store_dwordx4 v8, v[12:15], s[30:31]
	s_add_u32 s30, s30, s24
	s_addc_u32 s31, s31, 0
	v_cvt_pk_bf16_f32 v16, v97, v101
	v_cvt_pk_bf16_f32 v17, v105, v109
	v_cvt_pk_bf16_f32 v18, v113, v117
	v_cvt_pk_bf16_f32 v19, v121, v125
	global_store_dwordx4 v8, v[16:19], s[30:31]
	s_add_u32 s30, s30, s24
	s_addc_u32 s31, s31, 0
	v_cvt_pk_bf16_f32 v12, v98, v102
	v_cvt_pk_bf16_f32 v13, v106, v110
	v_cvt_pk_bf16_f32 v14, v114, v118
	v_cvt_pk_bf16_f32 v15, v122, v126
	global_store_dwordx4 v8, v[12:15], s[30:31]
	s_add_u32 s30, s30, s24
	s_addc_u32 s31, s31, 0
	v_cvt_pk_bf16_f32 v16, v99, v103
	v_cvt_pk_bf16_f32 v17, v107, v111
	v_cvt_pk_bf16_f32 v18, v115, v119
	v_cvt_pk_bf16_f32 v19, v123, v127
	global_store_dwordx4 v8, v[16:19], s[30:31]
	s_mov_b32 s4, s5
.Lp1t_loop:
	s_add_i32 s5, s4, 0x400
	s_cmpk_gt_i32 s5, 0x7d7f
	s_cbranch_scc1 .Lp1t_tail_b
	s_mov_b32 s16, 0x7580
	s_movk_i32 s15, 0x98
	s_mov_b32 s11, 13
	s_mov_b32 s12, 6
	s_mov_b32 s13, 11
	s_mov_b32 s14, 61603840
	s_cmpk_lt_u32 s5, 0x7580
	s_cselect_b32 s16, 0x7480, s16
	s_cselect_b32 s15, 0x88, s15
	s_cselect_b32 s11, 13, s11
	s_cselect_b32 s12, 6, s12
	s_cselect_b32 s13, 8, s13
	s_cselect_b32 s14, 61079552, s14
	s_cmpk_lt_u32 s5, 0x7480
	s_cselect_b32 s16, 0x5480, s16
	s_cselect_b32 s15, 0x78, s15
	s_cselect_b32 s11, 13, s11
	s_cselect_b32 s12, 6, s12
	s_cselect_b32 s13, 13, s13
	s_cselect_b32 s14, 44302336, s14
	s_cmpk_lt_u32 s5, 0x5480
	s_cselect_b32 s16, 0x3480, s16
	s_cselect_b32 s15, 0x70, s15
	s_cselect_b32 s11, 15, s11
	s_cselect_b32 s12, 8, s12
	s_cselect_b32 s13, 11, s13
	s_cselect_b32 s14, 27525120, s14
	s_cmpk_lt_u32 s5, 0x3480
	s_cselect_b32 s16, 0x2c80, s16
	s_cselect_b32 s15, 0x58, s15
	s_cselect_b32 s11, 13, s11
	s_cselect_b32 s12, 6, s12
	s_cselect_b32 s13, 11, s13
	s_cselect_b32 s14, 23330816, s14
	s_cmpk_lt_u32 s5, 0x2c80
	s_cselect_b32 s16, 0x2880, s16
	s_cselect_b32 s15, 0x50, s15
	s_cselect_b32 s11, 13, s11
	s_cselect_b32 s12, 6, s12
	s_cselect_b32 s13, 10, s13
	s_cselect_b32 s14, 21233664, s14
	s_cmpk_lt_u32 s5, 0x2880
	s_cselect_b32 s16, 0x2480, s16
	s_cselect_b32 s15, 0x48, s15
	s_cselect_b32 s11, 13, s11
	s_cselect_b32 s12, 6, s12
	s_cselect_b32 s13, 10, s13
	s_cselect_b32 s14, 19136512, s14
	s_load_dwordx2 s[6:7], s[0:1], s15
	s_sub_i32 s16, s5, s16
	s_lshl_b32 s19, 1, s12
	s_sub_i32 s19, s19, 1
	s_and_b32 s18, s16, s19
	s_lshr_b32 s17, s16, s12
	s_lshl_b32 s17, s17, 6
	s_lshl_b32 s19, s17, s11
	s_lshl_b32 s29, s18, 7
	s_add_u32 s19, s19, s29
	s_lshl_b32 s10, 2, s11
	v_lshlrev_b32_e32 v6, s11, v0
	v_add_u32_e32 v6, v6, v1
	s_lshl_b32 s29, s18, 5
	s_lshl_b32 s29, s29, s13
	s_add_u32 s29, s29, s17
	s_add_u32 s29, s29, s14
	s_lshl_b32 s29, s29, 1
	s_add_u32 s22, s20, s29
	s_addc_u32 s23, s21, 0
	s_lshl_b32 s24, 16, s13
	s_add_i32 s29, s13, 1
	v_lshlrev_b32_e32 v8, s29, v2
	v_add_u32_e32 v8, v8, v3
	s_waitcnt lgkmcnt(0)
; #define LAS __attribute__((address_space(3)))
; __device__ __forceinline__ unsigned pk2(float lo, float hi) { return pg8::cvt_pk_bf16(lo, hi); }
; template <int KIND> __device__ __forceinline__ void tr_item(const float* __restrict__ W, int K, int Nsrc, const float* __restrict__ gk, bf16_t* WT, LAS float* scr, int item, int nblk, int lane) {
;     ...
;     for (int i = 0; i < 32; ++i) { const int kk = 2 * i + (lane >> 5); float v = 0.f; if (src >= 0) v = __builtin_nontemporal_load(&W[(size_t)(k0 + kk) * Nsrc + src]); if (gk) v *= gk[k0 + kk]; scr[kk * 33 + (lane & 31)] = v; }
;     asm volatile("s_waitcnt lgkmcnt(0)" ::: "memory");
;     const int c = lane & 7;
; #pragma unroll
;     for (int j = 0; j < 4; ++j) { const int n = (lane >> 3) + 8 * j; const LAS float* s = scr + (8 * c) * 33 + n;
;         u32x4 o; o.x = pk2(s[0 * 33], s[1 * 33]); o.y = pk2(s[2 * 33], s[3 * 33]); o.z = pk2(s[4 * 33], s[5 * 33]); o.w = pk2(s[6 * 33], s[7 * 33]);
;         *(u32x4*)(WT + (size_t)(n0 + n) * K + k0 + 8 * c) = o; }
	s_add_u32 s8, s6, s19
	s_addc_u32 s9, s7, 0
	global_load_dword v32, v6, s[8:9] nt
	s_add_u32 s8, s8, s10
	s_addc_u32 s9, s9, 0
	global_load_dword v33, v6, s[8:9] nt
	s_add_u32 s8, s8, s10
	s_addc_u32 s9, s9, 0
	global_load_dword v34, v6, s[8:9] nt
	s_add_u32 s8, s8, s10
	s_addc_u32 s9, s9, 0
	global_load_dword v35, v6, s[8:9] nt
	s_add_u32 s8, s8, s10
	s_addc_u32 s9, s9, 0
	global_load_dword v36, v6, s[8:9] nt
	s_add_u32 s8, s8, s10
	s_addc_u32 s9, s9, 0
	global_load_dword v37, v6, s[8:9] nt
	s_add_u32 s8, s8, s10
	s_addc_u32 s9, s9, 0
	global_load_dword v38, v6, s[8:9] nt
	s_add_u32 s8, s8, s10
	s_addc_u32 s9, s9, 0
	global_load_dword v39, v6, s[8:9] nt
	s_add_u32 s8, s8, s10
	s_addc_u32 s9, s9, 0
	global_load_dword v40, v6, s[8:9] nt
	s_add_u32 s8, s8, s10
	s_addc_u32 s9, s9, 0
	global_load_dword v41, v6, s[8:9] nt
	s_add_u32 s8, s8, s10
	s_addc_u32 s9, s9, 0
	global_load_dword v42, v6, s[8:9] nt
	s_add_u32 s8, s8, s10
	s_addc_u32 s9, s9, 0
	global_load_dword v43, v6, s[8:9] nt
	s_add_u32 s8, s8, s10
	s_addc_u32 s9, s9, 0
	global_load_dword v44, v6, s[8:9] nt
	s_add_u32 s8, s8, s10
	s_addc_u32 s9, s9, 0
	global_load_dword v45, v6, s[8:9] nt
	s_add_u32 s8, s8, s10
	s_addc_u32 s9, s9, 0
	global_load_dword v46, v6, s[8:9] nt
	s_add_u32 s8, s8, s10
	s_addc_u32 s9, s9, 0
	global_load_dword v47, v6, s[8:9] nt
	s_add_u32 s8, s8, s10
	s_addc_u32 s9, s9, 0
	global_load_dword v48, v6, s[8:9] nt
	s_add_u32 s8, s8, s10
	s_addc_u32 s9, s9, 0
	global_load_dword v49, v6, s[8:9] nt
	s_add_u32 s8, s8, s10
	s_addc_u32 s9, s9, 0
	global_load_dword v50, v6, s[8:9] nt
	s_add_u32 s8, s8, s10
	s_addc_u32 s9, s9, 0
	global_load_dword v51, v6, s[8:9] nt
	s_add_u32 s8, s8, s10
	s_addc_u32 s9, s9, 0
	global_load_dword v52, v6, s[8:9] nt
	s_add_u32 s8, s8, s10
	s_addc_u32 s9, s9, 0
	global_load_dword v53, v6, s[8:9] nt
	s_add_u32 s8, s8, s10
	s_addc_u32 s9, s9, 0
	global_load_dword v54, v6, s[8:9] nt
	s_add_u32 s8, s8, s10
	s_addc_u32 s9, s9, 0
	global_load_dword v55, v6, s[8:9] nt
	s_add_u32 s8, s8, s10
	s_addc_u32 s9, s9, 0
	global_load_dword v56, v6, s[8:9] nt
	s_add_u32 s8, s8, s10
	s_addc_u32 s9, s9, 0
	global_load_dword v57, v6, s[8:9] nt
	s_add_u32 s8, s8, s10
	s_addc_u32 s9, s9, 0
	global_load_dword v58, v6, s[8:9] nt
	s_add_u32 s8, s8, s10
	s_addc_u32 s9, s9, 0
	global_load_dword v59, v6, s[8:9] nt
	s_add_u32 s8, s8, s10
	s_addc_u32 s9, s9, 0
	global_load_dword v60, v6, s[8:9] nt
	s_add_u32 s8, s8, s10
	s_addc_u32 s9, s9, 0
	global_load_dword v61, v6, s[8:9] nt
	s_add_u32 s8, s8, s10
	s_addc_u32 s9, s9, 0
	global_load_dword v62, v6, s[8:9] nt
	s_add_u32 s8, s8, s10
	s_addc_u32 s9, s9, 0
	global_load_dword v63, v6, s[8:9] nt
	s_mov_b64 s[30:31], s[26:27]
	s_waitcnt vmcnt(63)
	ds_write_b32 v4, v64
	s_waitcnt vmcnt(63)
	ds_write_b32 v4, v65 offset:264
	s_waitcnt vmcnt(63)
	ds_write_b32 v4, v66 offset:528
	s_waitcnt vmcnt(63)
	ds_write_b32 v4, v67 offset:792
	s_waitcnt vmcnt(63)
	ds_write_b32 v4, v68 offset:1056
	s_waitcnt vmcnt(62)
	ds_write_b32 v4, v69 offset:1320
	s_waitcnt vmcnt(61)
	ds_write_b32 v4, v70 offset:1584
	s_waitcnt vmcnt(60)
	ds_write_b32 v4, v71 offset:1848
	s_waitcnt vmcnt(59)
	ds_write_b32 v4, v72 offset:2112
	s_waitcnt vmcnt(58)
	ds_write_b32 v4, v73 offset:2376
	s_waitcnt vmcnt(57)
	ds_write_b32 v4, v74 offset:2640
	s_waitcnt vmcnt(56)
	ds_write_b32 v4, v75 offset:2904
	s_waitcnt vmcnt(55)
	ds_write_b32 v4, v76 offset:3168
	s_waitcnt vmcnt(54)
	ds_write_b32 v4, v77 offset:3432
	s_waitcnt vmcnt(53)
	ds_write_b32 v4, v78 offset:3696
	s_waitcnt vmcnt(52)
	ds_write_b32 v4, v79 offset:3960
	s_waitcnt vmcnt(51)
	ds_write_b32 v4, v80 offset:4224
	s_waitcnt vmcnt(50)
	ds_write_b32 v4, v81 offset:4488
	s_waitcnt vmcnt(49)
	ds_write_b32 v4, v82 offset:4752
	s_waitcnt vmcnt(48)
	ds_write_b32 v4, v83 offset:5016
	s_waitcnt vmcnt(47)
	ds_write_b32 v4, v84 offset:5280
	s_waitcnt vmcnt(46)
	ds_write_b32 v4, v85 offset:5544
	s_waitcnt vmcnt(45)
	ds_write_b32 v4, v86 offset:5808
	s_waitcnt vmcnt(44)
	ds_write_b32 v4, v87 offset:6072
	s_waitcnt vmcnt(43)
	ds_write_b32 v4, v88 offset:6336
	s_waitcnt vmcnt(42)
	ds_write_b32 v4, v89 offset:6600
	s_waitcnt vmcnt(41)
	ds_write_b32 v4, v90 offset:6864
	s_waitcnt vmcnt(40)
	ds_write_b32 v4, v91 offset:7128
	s_waitcnt vmcnt(39)
	ds_write_b32 v4, v92 offset:7392
	s_waitcnt vmcnt(38)
	ds_write_b32 v4, v93 offset:7656
	s_waitcnt vmcnt(37)
	ds_write_b32 v4, v94 offset:7920
	s_waitcnt vmcnt(36)
	ds_write_b32 v4, v95 offset:8184
	s_waitcnt lgkmcnt(0)
	ds_read2_b32 v[96:97], v5 offset0:0 offset1:8
	ds_read2_b32 v[98:99], v5 offset0:16 offset1:24
	ds_read2_b32 v[100:101], v5 offset0:33 offset1:41
	ds_read2_b32 v[102:103], v5 offset0:49 offset1:57
	ds_read2_b32 v[104:105], v5 offset0:66 offset1:74
	ds_read2_b32 v[106:107], v5 offset0:82 offset1:90
	ds_read2_b32 v[108:109], v5 offset0:99 offset1:107
	ds_read2_b32 v[110:111], v5 offset0:115 offset1:123
	ds_read2_b32 v[112:113], v5 offset0:132 offset1:140
	ds_read2_b32 v[114:115], v5 offset0:148 offset1:156
	ds_read2_b32 v[116:117], v5 offset0:165 offset1:173
	ds_read2_b32 v[118:119], v5 offset0:181 offset1:189
	ds_read2_b32 v[120:121], v5 offset0:198 offset1:206
	ds_read2_b32 v[122:123], v5 offset0:214 offset1:222
	ds_read2_b32 v[124:125], v5 offset0:231 offset1:239
	ds_read2_b32 v[126:127], v5 offset0:247 offset1:255
	s_waitcnt lgkmcnt(0)
	v_cvt_pk_bf16_f32 v12, v96, v100
	v_cvt_pk_bf16_f32 v13, v104, v108
	v_cvt_pk_bf16_f32 v14, v112, v116
	v_cvt_pk_bf16_f32 v15, v120, v124
	global_store_dwordx4 v9, v[12:15], s[30:31]
	s_add_u32 s30, s30, s28
	s_addc_u32 s31, s31, 0
	v_cvt_pk_bf16_f32 v16, v97, v101
	v_cvt_pk_bf16_f32 v17, v105, v109
	v_cvt_pk_bf16_f32 v18, v113, v117
	v_cvt_pk_bf16_f32 v19, v121, v125
	global_store_dwordx4 v9, v[16:19], s[30:31]
	s_add_u32 s30, s30, s28
	s_addc_u32 s31, s31, 0
	v_cvt_pk_bf16_f32 v12, v98, v102
	v_cvt_pk_bf16_f32 v13, v106, v110
	v_cvt_pk_bf16_f32 v14, v114, v118
	v_cvt_pk_bf16_f32 v15, v122, v126
	global_store_dwordx4 v9, v[12:15], s[30:31]
	s_add_u32 s30, s30, s28
	s_addc_u32 s31, s31, 0
	v_cvt_pk_bf16_f32 v16, v99, v103
	v_cvt_pk_bf16_f32 v17, v107, v111
	v_cvt_pk_bf16_f32 v18, v115, v119
	v_cvt_pk_bf16_f32 v19, v123, v127
	global_store_dwordx4 v9, v[16:19], s[30:31]
	s_mov_b32 s4, s5
	s_add_i32 s5, s4, 0x400
	s_cmpk_gt_i32 s5, 0x7d7f
	s_cbranch_scc1 .Lp1t_tail_a
; #define LAS __attribute__((address_space(3)))
; template <int KIND> __device__ __forceinline__ void tr_item(const float* __restrict__ W, int K, int Nsrc, const float* __restrict__ gk, bf16_t* WT, LAS float* scr, int item, int nblk, int lane) {
;     const int kb = item / nblk, nb = item - kb * nblk, k0 = 64 * kb, n0 = 32 * nb;
;     const int src = srcmap<KIND>(n0 + (lane & 31));
; #pragma unroll 8
;     for (int i = 0; i < 32; ++i) { const int kk = 2 * i + (lane >> 5); float v = 0.f; if (src >= 0) v = __builtin_nontemporal_load(&W[(size_t)(k0 + kk) * Nsrc + src]); if (gk) v *= gk[k0 + kk]; scr[kk * 33 + (lane & 31)] = v; }
	s_mov_b32 s16, 0x7580
	s_movk_i32 s15, 0x98
	s_mov_b32 s11, 13
	s_mov_b32 s12, 6
	s_mov_b32 s13, 11
	s_mov_b32 s14, 61603840
	s_cmpk_lt_u32 s5, 0x7580
	s_cselect_b32 s16, 0x7480, s16
	s_cselect_b32 s15, 0x88, s15
	s_cselect_b32 s11, 13, s11
	s_cselect_b32 s12, 6, s12
	s_cselect_b32 s13, 8, s13
	s_cselect_b32 s14, 61079552, s14
	s_cmpk_lt_u32 s5, 0x7480
	s_cselect_b32 s16, 0x5480, s16
	s_cselect_b32 s15, 0x78, s15
	s_cselect_b32 s11, 13, s11
	s_cselect_b32 s12, 6, s12
	s_cselect_b32 s13, 13, s13
	s_cselect_b32 s14, 44302336, s14
	s_cmpk_lt_u32 s5, 0x5480
	s_cselect_b32 s16, 0x3480, s16
	s_cselect_b32 s15, 0x70, s15
	s_cselect_b32 s11, 15, s11
	s_cselect_b32 s12, 8, s12
	s_cselect_b32 s13, 11, s13
	s_cselect_b32 s14, 27525120, s14
	s_cmpk_lt_u32 s5, 0x3480
	s_cselect_b32 s16, 0x2c80, s16
	s_cselect_b32 s15, 0x58, s15
	s_cselect_b32 s11, 13, s11
	s_cselect_b32 s12, 6, s12
	s_cselect_b32 s13, 11, s13
	s_cselect_b32 s14, 23330816, s14
	s_cmpk_lt_u32 s5, 0x2c80
	s_cselect_b32 s16, 0x2880, s16
	s_cselect_b32 s15, 0x50, s15
	s_cselect_b32 s11, 13, s11
	s_cselect_b32 s12, 6, s12
	s_cselect_b32 s13, 10, s13
	s_cselect_b32 s14, 21233664, s14
	s_cmpk_lt_u32 s5, 0x2880
	s_cselect_b32 s16, 0x2480, s16
	s_cselect_b32 s15, 0x48, s15
	s_cselect_b32 s11, 13, s11
	s_cselect_b32 s12, 6, s12
	s_cselect_b32 s13, 10, s13
	s_cselect_b32 s14, 19136512, s14
	s_load_dwordx2 s[6:7], s[0:1], s15
	s_sub_i32 s16, s5, s16
	s_lshl_b32 s19, 1, s12
	s_sub_i32 s19, s19, 1
	s_and_b32 s18, s16, s19
	s_lshr_b32 s17, s16, s12
	s_lshl_b32 s17, s17, 6
	s_lshl_b32 s19, s17, s11
	s_lshl_b32 s29, s18, 7
	s_add_u32 s19, s19, s29
	s_lshl_b32 s10, 2, s11
	v_lshlrev_b32_e32 v6, s11, v0
	v_add_u32_e32 v6, v6, v1
	s_lshl_b32 s29, s18, 5
	s_lshl_b32 s29, s29, s13
	s_add_u32 s29, s29, s17
	s_add_u32 s29, s29, s14
	s_lshl_b32 s29, s29, 1
	s_add_u32 s26, s20, s29
	s_addc_u32 s27, s21, 0
	s_lshl_b32 s28, 16, s13
	s_add_i32 s29, s13, 1
	v_lshlrev_b32_e32 v9, s29, v2
	v_add_u32_e32 v9, v9, v3
	s_waitcnt lgkmcnt(0)
	s_add_u32 s8, s6, s19
	s_addc_u32 s9, s7, 0
	global_load_dword v64, v6, s[8:9] nt
	s_add_u32 s8, s8, s10
	s_addc_u32 s9, s9, 0
	global_load_dword v65, v6, s[8:9] nt
	s_add_u32 s8, s8, s10
	s_addc_u32 s9, s9, 0
	global_load_dword v66, v6, s[8:9] nt
	s_add_u32 s8, s8, s10
	s_addc_u32 s9, s9, 0
	global_load_dword v67, v6, s[8:9] nt
	s_add_u32 s8, s8, s10
	s_addc_u32 s9, s9, 0
	global_load_dword v68, v6, s[8:9] nt
	s_add_u32 s8, s8, s10
	s_addc_u32 s9, s9, 0
	global_load_dword v69, v6, s[8:9] nt
	s_add_u32 s8, s8, s10
	s_addc_u32 s9, s9, 0
	global_load_dword v70, v6, s[8:9] nt
	s_add_u32 s8, s8, s10
	s_addc_u32 s9, s9, 0
	global_load_dword v71, v6, s[8:9] nt
	s_add_u32 s8, s8, s10
	s_addc_u32 s9, s9, 0
	global_load_dword v72, v6, s[8:9] nt
	s_add_u32 s8, s8, s10
	s_addc_u32 s9, s9, 0
	global_load_dword v73, v6, s[8:9] nt
	s_add_u32 s8, s8, s10
	s_addc_u32 s9, s9, 0
	global_load_dword v74, v6, s[8:9] nt
	s_add_u32 s8, s8, s10
	s_addc_u32 s9, s9, 0
	global_load_dword v75, v6, s[8:9] nt
	s_add_u32 s8, s8, s10
	s_addc_u32 s9, s9, 0
	global_load_dword v76, v6, s[8:9] nt
	s_add_u32 s8, s8, s10
	s_addc_u32 s9, s9, 0
	global_load_dword v77, v6, s[8:9] nt
	s_add_u32 s8, s8, s10
	s_addc_u32 s9, s9, 0
	global_load_dword v78, v6, s[8:9] nt
	s_add_u32 s8, s8, s10
	s_addc_u32 s9, s9, 0
	global_load_dword v79, v6, s[8:9] nt
	s_add_u32 s8, s8, s10
	s_addc_u32 s9, s9, 0
	global_load_dword v80, v6, s[8:9] nt
	s_add_u32 s8, s8, s10
	s_addc_u32 s9, s9, 0
	global_load_dword v81, v6, s[8:9] nt
	s_add_u32 s8, s8, s10
	s_addc_u32 s9, s9, 0
	global_load_dword v82, v6, s[8:9] nt
	s_add_u32 s8, s8, s10
	s_addc_u32 s9, s9, 0
	global_load_dword v83, v6, s[8:9] nt
	s_add_u32 s8, s8, s10
	s_addc_u32 s9, s9, 0
	global_load_dword v84, v6, s[8:9] nt
	s_add_u32 s8, s8, s10
	s_addc_u32 s9, s9, 0
	global_load_dword v85, v6, s[8:9] nt
	s_add_u32 s8, s8, s10
	s_addc_u32 s9, s9, 0
	global_load_dword v86, v6, s[8:9] nt
	s_add_u32 s8, s8, s10
	s_addc_u32 s9, s9, 0
	global_load_dword v87, v6, s[8:9] nt
	s_add_u32 s8, s8, s10
	s_addc_u32 s9, s9, 0
	global_load_dword v88, v6, s[8:9] nt
	s_add_u32 s8, s8, s10
	s_addc_u32 s9, s9, 0
	global_load_dword v89, v6, s[8:9] nt
	s_add_u32 s8, s8, s10
	s_addc_u32 s9, s9, 0
	global_load_dword v90, v6, s[8:9] nt
	s_add_u32 s8, s8, s10
	s_addc_u32 s9, s9, 0
	global_load_dword v91, v6, s[8:9] nt
	s_add_u32 s8, s8, s10
	s_addc_u32 s9, s9, 0
	global_load_dword v92, v6, s[8:9] nt
	s_add_u32 s8, s8, s10
	s_addc_u32 s9, s9, 0
	global_load_dword v93, v6, s[8:9] nt
	s_add_u32 s8, s8, s10
	s_addc_u32 s9, s9, 0
	global_load_dword v94, v6, s[8:9] nt
	s_add_u32 s8, s8, s10
	s_addc_u32 s9, s9, 0
	global_load_dword v95, v6, s[8:9] nt
	s_mov_b64 s[30:31], s[22:23]
	s_waitcnt vmcnt(63)
; #define LAS __attribute__((address_space(3)))
; __device__ __forceinline__ unsigned pk2(float lo, float hi) { return pg8::cvt_pk_bf16(lo, hi); }
; template <int KIND> __device__ __forceinline__ void tr_item(const float* __restrict__ W, int K, int Nsrc, const float* __restrict__ gk, bf16_t* WT, LAS float* scr, int item, int nblk, int lane) {
;     ...
;     for (int i = 0; i < 32; ++i) { const int kk = 2 * i + (lane >> 5); float v = 0.f; if (src >= 0) v = __builtin_nontemporal_load(&W[(size_t)(k0 + kk) * Nsrc + src]); if (gk) v *= gk[k0 + kk]; scr[kk * 33 + (lane & 31)] = v; }
;     asm volatile("s_waitcnt lgkmcnt(0)" ::: "memory");
;     const int c = lane & 7;
; #pragma unroll
;     for (int j = 0; j < 4; ++j) { const int n = (lane >> 3) + 8 * j; const LAS float* s = scr + (8 * c) * 33 + n;
;         u32x4 o; o.x = pk2(s[0 * 33], s[1 * 33]); o.y = pk2(s[2 * 33], s[3 * 33]); o.z = pk2(s[4 * 33], s[5 * 33]); o.w = pk2(s[6 * 33], s[7 * 33]);
;         *(u32x4*)(WT + (size_t)(n0 + n) * K + k0 + 8 * c) = o; }
	ds_write_b32 v4, v32
	s_waitcnt vmcnt(63)
	ds_write_b32 v4, v33 offset:264
	s_waitcnt vmcnt(63)
	ds_write_b32 v4, v34 offset:528
	s_waitcnt vmcnt(63)
	ds_write_b32 v4, v35 offset:792
	s_waitcnt vmcnt(63)
	ds_write_b32 v4, v36 offset:1056
	s_waitcnt vmcnt(62)
	ds_write_b32 v4, v37 offset:1320
	s_waitcnt vmcnt(61)
	ds_write_b32 v4, v38 offset:1584
	s_waitcnt vmcnt(60)
	ds_write_b32 v4, v39 offset:1848
	s_waitcnt vmcnt(59)
	ds_write_b32 v4, v40 offset:2112
	s_waitcnt vmcnt(58)
	ds_write_b32 v4, v41 offset:2376
	s_waitcnt vmcnt(57)
	ds_write_b32 v4, v42 offset:2640
	s_waitcnt vmcnt(56)
	ds_write_b32 v4, v43 offset:2904
	s_waitcnt vmcnt(55)
	ds_write_b32 v4, v44 offset:3168
	s_waitcnt vmcnt(54)
	ds_write_b32 v4, v45 offset:3432
	s_waitcnt vmcnt(53)
	ds_write_b32 v4, v46 offset:3696
	s_waitcnt vmcnt(52)
	ds_write_b32 v4, v47 offset:3960
	s_waitcnt vmcnt(51)
	ds_write_b32 v4, v48 offset:4224
	s_waitcnt vmcnt(50)
	ds_write_b32 v4, v49 offset:4488
	s_waitcnt vmcnt(49)
	ds_write_b32 v4, v50 offset:4752
	s_waitcnt vmcnt(48)
	ds_write_b32 v4, v51 offset:5016
	s_waitcnt vmcnt(47)
	ds_write_b32 v4, v52 offset:5280
	s_waitcnt vmcnt(46)
	ds_write_b32 v4, v53 offset:5544
	s_waitcnt vmcnt(45)
	ds_write_b32 v4, v54 offset:5808
	s_waitcnt vmcnt(44)
	ds_write_b32 v4, v55 offset:6072
	s_waitcnt vmcnt(43)
	ds_write_b32 v4, v56 offset:6336
	s_waitcnt vmcnt(42)
	ds_write_b32 v4, v57 offset:6600
	s_waitcnt vmcnt(41)
	ds_write_b32 v4, v58 offset:6864
	s_waitcnt vmcnt(40)
	ds_write_b32 v4, v59 offset:7128
	s_waitcnt vmcnt(39)
	ds_write_b32 v4, v60 offset:7392
	s_waitcnt vmcnt(38)
	ds_write_b32 v4, v61 offset:7656
	s_waitcnt vmcnt(37)
	ds_write_b32 v4, v62 offset:7920
	s_waitcnt vmcnt(36)
	ds_write_b32 v4, v63 offset:8184
	s_waitcnt lgkmcnt(0)
	ds_read2_b32 v[96:97], v5 offset0:0 offset1:8
	ds_read2_b32 v[98:99], v5 offset0:16 offset1:24
	ds_read2_b32 v[100:101], v5 offset0:33 offset1:41
	ds_read2_b32 v[102:103], v5 offset0:49 offset1:57
	ds_read2_b32 v[104:105], v5 offset0:66 offset1:74
	ds_read2_b32 v[106:107], v5 offset0:82 offset1:90
	ds_read2_b32 v[108:109], v5 offset0:99 offset1:107
	ds_read2_b32 v[110:111], v5 offset0:115 offset1:123
	ds_read2_b32 v[112:113], v5 offset0:132 offset1:140
	ds_read2_b32 v[114:115], v5 offset0:148 offset1:156
	ds_read2_b32 v[116:117], v5 offset0:165 offset1:173
	ds_read2_b32 v[118:119], v5 offset0:181 offset1:189
	ds_read2_b32 v[120:121], v5 offset0:198 offset1:206
	ds_read2_b32 v[122:123], v5 offset0:214 offset1:222
	ds_read2_b32 v[124:125], v5 offset0:231 offset1:239
	ds_read2_b32 v[126:127], v5 offset0:247 offset1:255
	s_waitcnt lgkmcnt(0)
	v_cvt_pk_bf16_f32 v12, v96, v100
	v_cvt_pk_bf16_f32 v13, v104, v108
	v_cvt_pk_bf16_f32 v14, v112, v116
	v_cvt_pk_bf16_f32 v15, v120, v124
	global_store_dwordx4 v8, v[12:15], s[30:31]
	s_add_u32 s30, s30, s24
	s_addc_u32 s31, s31, 0
	v_cvt_pk_bf16_f32 v16, v97, v101
	v_cvt_pk_bf16_f32 v17, v105, v109
	v_cvt_pk_bf16_f32 v18, v113, v117
	v_cvt_pk_bf16_f32 v19, v121, v125
	global_store_dwordx4 v8, v[16:19], s[30:31]
	s_add_u32 s30, s30, s24
	s_addc_u32 s31, s31, 0
	v_cvt_pk_bf16_f32 v12, v98, v102
	v_cvt_pk_bf16_f32 v13, v106, v110
	v_cvt_pk_bf16_f32 v14, v114, v118
	v_cvt_pk_bf16_f32 v15, v122, v126
	global_store_dwordx4 v8, v[12:15], s[30:31]
	s_add_u32 s30, s30, s24
	s_addc_u32 s31, s31, 0
	v_cvt_pk_bf16_f32 v16, v99, v103
	v_cvt_pk_bf16_f32 v17, v107, v111
	v_cvt_pk_bf16_f32 v18, v115, v119
	v_cvt_pk_bf16_f32 v19, v123, v127
	global_store_dwordx4 v8, v[16:19], s[30:31]
	s_mov_b32 s4, s5
	s_branch .Lp1t_loop

; #define PG8_WAIT_V(n) asm volatile("s_waitcnt vmcnt(" #n ")" ::: "memory")
; #define PG8_BAR __builtin_amdgcn_s_barrier()
; template <class Epi, class Sched, bool ALIGN_EPI = false, bool SP2 = false>
; __device__ __forceinline__ void gemm_phase(PG8_LAS unsigned char* lds, const Gemm g, const Sched& S, const Epi& E) {
;     ...
;     PG8_WAIT_V(0);
;     if constexpr (!ALIGN_EPI) { if (wr == 0) PG8_BAR; }
;     PG8_BAR;
.Lp1t_skip:
	v_readlane_b32 s70, v246, 6
	v_readlane_b32 s71, v246, 7
	s_mov_b32 s72, s77
	s_barrier
